# stack_plus_midblock_setprio_pair_removed
# speedup vs baseline: 1.0086x; 1.0013x over previous
.LBB0_220:
	s_add_u32 s50, s14, 0x100
	s_addc_u32 s51, s15, 0
	s_and_b64 s[52:53], s[52:53], exec
	s_cselect_b32 s55, s58, s51
	s_cselect_b32 s54, s59, s50
	s_cselect_b32 s53, s43, s80
	s_cselect_b32 s52, s77, s79
	s_add_i32 s82, 0, 0x10000
	v_add_u32_e32 v0, s82, v187
	s_add_i32 s83, 0, 0x14000
	ds_read_b128 v[130:133], v0
	ds_read_b128 v[134:137], v0 offset:1024
	ds_read_b128 v[176:179], v0 offset:2048
	ds_read_b128 v[180:183], v0 offset:3072
	v_add_u32_e32 v0, s83, v187
	ds_read_b128 v[192:195], v0
	ds_read_b128 v[196:199], v0 offset:1024
	ds_read_b128 v[200:203], v0 offset:2048
	ds_read_b128 v[204:207], v0 offset:3072
	v_lshl_add_u64 v[184:185], s[14:15], 0, v[172:173]
	s_add_i32 m0, s66, 0xc000
	ds_read_b128 v[208:211], v190
	ds_read_b128 v[212:215], v190 offset:1024
	ds_read_b128 v[226:229], v190 offset:2048
	ds_read_b128 v[230:233], v190 offset:3072
	ds_read_b128 v[234:237], v190 offset:4096
	ds_read_b128 v[238:241], v190 offset:5120
	ds_read_b128 v[242:245], v190 offset:6144
	ds_read_b128 v[246:249], v190 offset:7168
	global_load_lds_dwordx4 v[184:185], off
	v_lshl_add_u64 v[184:185], s[14:15], 0, v[174:175]
	s_add_i32 m0, s66, 0xe000
	s_nop 0
	global_load_lds_dwordx4 v[184:185], off
	s_waitcnt vmcnt(8)
	s_waitcnt lgkmcnt(0)
	s_barrier
	s_setprio 1
	v_mfma_f32_16x16x32_bf16 v[126:129], v[130:133], v[208:211], v[126:129]
	v_mfma_f32_16x16x32_bf16 v[122:125], v[176:179], v[208:211], v[122:125]
	v_mfma_f32_16x16x32_bf16 v[110:113], v[130:133], v[226:229], v[110:113]
	v_mfma_f32_16x16x32_bf16 v[106:109], v[176:179], v[226:229], v[106:109]
	v_mfma_f32_16x16x32_bf16 v[94:97], v[130:133], v[234:237], v[94:97]
	v_mfma_f32_16x16x32_bf16 v[90:93], v[176:179], v[234:237], v[90:93]
	v_mfma_f32_16x16x32_bf16 v[78:81], v[130:133], v[242:245], v[78:81]
	v_mfma_f32_16x16x32_bf16 v[74:77], v[176:179], v[242:245], v[74:77]
	v_mfma_f32_16x16x32_bf16 v[126:129], v[134:137], v[212:215], v[126:129]
	v_mfma_f32_16x16x32_bf16 v[122:125], v[180:183], v[212:215], v[122:125]
	v_mfma_f32_16x16x32_bf16 v[110:113], v[134:137], v[230:233], v[110:113]
	v_mfma_f32_16x16x32_bf16 v[106:109], v[180:183], v[230:233], v[106:109]
	v_mfma_f32_16x16x32_bf16 v[94:97], v[134:137], v[238:241], v[94:97]
	v_mfma_f32_16x16x32_bf16 v[90:93], v[180:183], v[238:241], v[90:93]
	v_mfma_f32_16x16x32_bf16 v[78:81], v[134:137], v[246:249], v[78:81]
	v_mfma_f32_16x16x32_bf16 v[74:77], v[180:183], v[246:249], v[74:77]
	v_mfma_f32_16x16x32_bf16 v[118:121], v[192:195], v[208:211], v[118:121]
	v_mfma_f32_16x16x32_bf16 v[114:117], v[200:203], v[208:211], v[114:117]
	v_mfma_f32_16x16x32_bf16 v[102:105], v[192:195], v[226:229], v[102:105]
	v_mfma_f32_16x16x32_bf16 v[98:101], v[200:203], v[226:229], v[98:101]
	v_mfma_f32_16x16x32_bf16 v[86:89], v[192:195], v[234:237], v[86:89]
	v_mfma_f32_16x16x32_bf16 v[82:85], v[200:203], v[234:237], v[82:85]
	v_mfma_f32_16x16x32_bf16 v[70:73], v[192:195], v[242:245], v[70:73]
	v_mfma_f32_16x16x32_bf16 v[66:69], v[200:203], v[242:245], v[66:69]
	v_mfma_f32_16x16x32_bf16 v[118:121], v[196:199], v[212:215], v[118:121]
	v_mfma_f32_16x16x32_bf16 v[114:117], v[204:207], v[212:215], v[114:117]
	v_mfma_f32_16x16x32_bf16 v[102:105], v[196:199], v[230:233], v[102:105]
	v_mfma_f32_16x16x32_bf16 v[98:101], v[204:207], v[230:233], v[98:101]
	v_mfma_f32_16x16x32_bf16 v[86:89], v[196:199], v[238:241], v[86:89]
	v_mfma_f32_16x16x32_bf16 v[82:85], v[204:207], v[238:241], v[82:85]
	v_mfma_f32_16x16x32_bf16 v[70:73], v[196:199], v[246:249], v[70:73]
	v_mfma_f32_16x16x32_bf16 v[66:69], v[204:207], v[246:249], v[66:69]
	s_setprio 0
	s_barrier
	s_add_i32 s14, s82, s65
	v_lshl_add_u64 v[184:185], s[52:53], 0, v[140:141]
	s_mov_b32 m0, s14
	ds_read_b128 v[208:211], v190 offset:16384
	ds_read_b128 v[212:215], v190 offset:17408
	ds_read_b128 v[226:229], v190 offset:18432
	ds_read_b128 v[230:233], v190 offset:19456
	ds_read_b128 v[234:237], v190 offset:20480
	ds_read_b128 v[238:241], v190 offset:21504
	ds_read_b128 v[242:245], v190 offset:22528
	ds_read_b128 v[246:249], v190 offset:23552
	global_load_lds_dwordx4 v[184:185], off
	s_add_i32 m0, s14, 0x2000
	s_add_u32 s14, s52, 0x40000
	v_lshl_add_u64 v[216:217], s[52:53], 0, v[144:145]
	s_addc_u32 s15, s53, 0
	s_add_i32 s82, s83, s65
	global_load_lds_dwordx4 v[216:217], off
	v_lshl_add_u64 v[218:219], s[14:15], 0, v[140:141]
	s_mov_b32 m0, s82
	v_lshl_add_u64 v[220:221], s[54:55], 0, v[142:143]
	global_load_lds_dwordx4 v[218:219], off
	v_lshl_add_u64 v[218:219], s[14:15], 0, v[144:145]
	s_add_i32 m0, s82, 0x2000
	s_nop 0
	global_load_lds_dwordx4 v[218:219], off
	v_lshl_add_u64 v[218:219], s[54:55], 0, v[138:139]
	s_mov_b32 m0, s66
	s_nop 0
	global_load_lds_dwordx4 v[218:219], off
	s_mov_b32 m0, s67
	s_nop 0
	global_load_lds_dwordx4 v[220:221], off
	s_waitcnt vmcnt(8)
	s_waitcnt lgkmcnt(0)
	s_barrier
	s_setprio 1
	v_mfma_f32_16x16x32_bf16 v[62:65], v[130:133], v[208:211], v[62:65]
	v_mfma_f32_16x16x32_bf16 v[58:61], v[176:179], v[208:211], v[58:61]
	v_mfma_f32_16x16x32_bf16 v[46:49], v[130:133], v[226:229], v[46:49]
	v_mfma_f32_16x16x32_bf16 v[42:45], v[176:179], v[226:229], v[42:45]
	v_mfma_f32_16x16x32_bf16 v[30:33], v[130:133], v[234:237], v[30:33]
	v_mfma_f32_16x16x32_bf16 v[26:29], v[176:179], v[234:237], v[26:29]
	v_mfma_f32_16x16x32_bf16 v[14:17], v[130:133], v[242:245], v[14:17]
	v_mfma_f32_16x16x32_bf16 v[10:13], v[176:179], v[242:245], v[10:13]
	v_mfma_f32_16x16x32_bf16 v[62:65], v[134:137], v[212:215], v[62:65]
	v_mfma_f32_16x16x32_bf16 v[58:61], v[180:183], v[212:215], v[58:61]
	v_mfma_f32_16x16x32_bf16 v[46:49], v[134:137], v[230:233], v[46:49]
	v_mfma_f32_16x16x32_bf16 v[42:45], v[180:183], v[230:233], v[42:45]
	v_mfma_f32_16x16x32_bf16 v[30:33], v[134:137], v[238:241], v[30:33]
	v_mfma_f32_16x16x32_bf16 v[26:29], v[180:183], v[238:241], v[26:29]
	v_mfma_f32_16x16x32_bf16 v[14:17], v[134:137], v[246:249], v[14:17]
	v_mfma_f32_16x16x32_bf16 v[10:13], v[180:183], v[246:249], v[10:13]
	v_mfma_f32_16x16x32_bf16 v[54:57], v[192:195], v[208:211], v[54:57]
	v_mfma_f32_16x16x32_bf16 v[50:53], v[200:203], v[208:211], v[50:53]
	v_mfma_f32_16x16x32_bf16 v[38:41], v[192:195], v[226:229], v[38:41]
	v_mfma_f32_16x16x32_bf16 v[34:37], v[200:203], v[226:229], v[34:37]
	v_mfma_f32_16x16x32_bf16 v[22:25], v[192:195], v[234:237], v[22:25]
	v_mfma_f32_16x16x32_bf16 v[18:21], v[200:203], v[234:237], v[18:21]
	v_mfma_f32_16x16x32_bf16 v[6:9], v[192:195], v[242:245], v[6:9]
	v_mfma_f32_16x16x32_bf16 v[2:5], v[200:203], v[242:245], v[2:5]
	v_mfma_f32_16x16x32_bf16 v[54:57], v[196:199], v[212:215], v[54:57]
	v_mfma_f32_16x16x32_bf16 v[50:53], v[204:207], v[212:215], v[50:53]
	v_mfma_f32_16x16x32_bf16 v[38:41], v[196:199], v[230:233], v[38:41]
	v_mfma_f32_16x16x32_bf16 v[34:37], v[204:207], v[230:233], v[34:37]
	v_mfma_f32_16x16x32_bf16 v[22:25], v[196:199], v[238:241], v[22:25]
	v_mfma_f32_16x16x32_bf16 v[18:21], v[204:207], v[238:241], v[18:21]
	v_mfma_f32_16x16x32_bf16 v[6:9], v[196:199], v[246:249], v[6:9]
	v_mfma_f32_16x16x32_bf16 v[2:5], v[204:207], v[246:249], v[2:5]
	s_setprio 0
	s_barrier
	s_add_i32 s82, 0, 0x18000
	v_add_u32_e32 v0, s82, v187
	s_add_i32 s83, 0, 0x1c000
	ds_read_b128 v[130:133], v0
	ds_read_b128 v[134:137], v0 offset:1024
	ds_read_b128 v[176:179], v0 offset:2048
	ds_read_b128 v[180:183], v0 offset:3072
	v_add_u32_e32 v0, s83, v187
	ds_read_b128 v[192:195], v0
	ds_read_b128 v[196:199], v0 offset:1024
	ds_read_b128 v[200:203], v0 offset:2048
	ds_read_b128 v[204:207], v0 offset:3072
	s_add_u32 s14, s54, 0x40000
	s_addc_u32 s15, s55, 0
	s_mov_b32 m0, s68
	v_lshl_add_u64 v[250:251], s[14:15], 0, v[138:139]
	ds_read_b128 v[208:211], v190 offset:32768
	ds_read_b128 v[212:215], v190 offset:33792
	ds_read_b128 v[226:229], v190 offset:34816
	ds_read_b128 v[230:233], v190 offset:35840
	ds_read_b128 v[234:237], v190 offset:36864
	ds_read_b128 v[238:241], v190 offset:37888
	ds_read_b128 v[242:245], v190 offset:38912
	ds_read_b128 v[246:249], v190 offset:39936
	global_load_lds_dwordx4 v[250:251], off
	v_lshl_add_u64 v[250:251], s[14:15], 0, v[142:143]
	s_mov_b32 m0, s69
	s_nop 0
	global_load_lds_dwordx4 v[250:251], off
	s_waitcnt vmcnt(8)
	s_waitcnt lgkmcnt(0)
	s_barrier
	s_setprio 1
	v_mfma_f32_16x16x32_bf16 v[126:129], v[130:133], v[208:211], v[126:129]
	v_mfma_f32_16x16x32_bf16 v[122:125], v[176:179], v[208:211], v[122:125]
	v_mfma_f32_16x16x32_bf16 v[110:113], v[130:133], v[226:229], v[110:113]
	v_mfma_f32_16x16x32_bf16 v[106:109], v[176:179], v[226:229], v[106:109]
	v_mfma_f32_16x16x32_bf16 v[94:97], v[130:133], v[234:237], v[94:97]
	v_mfma_f32_16x16x32_bf16 v[90:93], v[176:179], v[234:237], v[90:93]
	v_mfma_f32_16x16x32_bf16 v[78:81], v[130:133], v[242:245], v[78:81]
	v_mfma_f32_16x16x32_bf16 v[74:77], v[176:179], v[242:245], v[74:77]
	v_mfma_f32_16x16x32_bf16 v[126:129], v[134:137], v[212:215], v[126:129]
	v_mfma_f32_16x16x32_bf16 v[122:125], v[180:183], v[212:215], v[122:125]
	v_mfma_f32_16x16x32_bf16 v[110:113], v[134:137], v[230:233], v[110:113]
	v_mfma_f32_16x16x32_bf16 v[106:109], v[180:183], v[230:233], v[106:109]
	v_mfma_f32_16x16x32_bf16 v[94:97], v[134:137], v[238:241], v[94:97]
	v_mfma_f32_16x16x32_bf16 v[90:93], v[180:183], v[238:241], v[90:93]
	v_mfma_f32_16x16x32_bf16 v[78:81], v[134:137], v[246:249], v[78:81]
	v_mfma_f32_16x16x32_bf16 v[74:77], v[180:183], v[246:249], v[74:77]
	v_mfma_f32_16x16x32_bf16 v[118:121], v[192:195], v[208:211], v[118:121]
	v_mfma_f32_16x16x32_bf16 v[114:117], v[200:203], v[208:211], v[114:117]
	v_mfma_f32_16x16x32_bf16 v[102:105], v[192:195], v[226:229], v[102:105]
	v_mfma_f32_16x16x32_bf16 v[98:101], v[200:203], v[226:229], v[98:101]
	v_mfma_f32_16x16x32_bf16 v[86:89], v[192:195], v[234:237], v[86:89]
	v_mfma_f32_16x16x32_bf16 v[82:85], v[200:203], v[234:237], v[82:85]
	v_mfma_f32_16x16x32_bf16 v[70:73], v[192:195], v[242:245], v[70:73]
	v_mfma_f32_16x16x32_bf16 v[66:69], v[200:203], v[242:245], v[66:69]
	v_mfma_f32_16x16x32_bf16 v[118:121], v[196:199], v[212:215], v[118:121]
	v_mfma_f32_16x16x32_bf16 v[114:117], v[204:207], v[212:215], v[114:117]
	v_mfma_f32_16x16x32_bf16 v[102:105], v[196:199], v[230:233], v[102:105]
	v_mfma_f32_16x16x32_bf16 v[98:101], v[204:207], v[230:233], v[98:101]
	v_mfma_f32_16x16x32_bf16 v[86:89], v[196:199], v[238:241], v[86:89]
	v_mfma_f32_16x16x32_bf16 v[82:85], v[204:207], v[238:241], v[82:85]
	v_mfma_f32_16x16x32_bf16 v[70:73], v[196:199], v[246:249], v[70:73]
	v_mfma_f32_16x16x32_bf16 v[66:69], v[204:207], v[246:249], v[66:69]
	s_setprio 0
	s_barrier
	s_mov_b64 s[54:55], 0x80
	s_add_i32 s14, s82, s65
	v_lshl_add_u64 v[184:185], v[184:185], 0, s[54:55]
	s_mov_b32 m0, s14
	ds_read_b128 v[208:211], v190 offset:49152
	ds_read_b128 v[212:215], v190 offset:50176
	ds_read_b128 v[226:229], v190 offset:51200
	ds_read_b128 v[230:233], v190 offset:52224
	ds_read_b128 v[234:237], v190 offset:53248
	ds_read_b128 v[238:241], v190 offset:54272
	ds_read_b128 v[242:245], v190 offset:55296
	ds_read_b128 v[246:249], v190 offset:56320
	global_load_lds_dwordx4 v[184:185], off
	s_add_i32 m0, s14, 0x2000
	s_add_u32 s14, s52, 0x40080
	v_lshl_add_u64 v[184:185], v[216:217], 0, s[54:55]
	s_addc_u32 s15, s53, 0
	s_add_i32 s52, s83, s65
	global_load_lds_dwordx4 v[184:185], off
	v_lshl_add_u64 v[184:185], s[14:15], 0, v[140:141]
	s_mov_b32 m0, s52
	s_mov_b64 s[82:83], 0x80
	global_load_lds_dwordx4 v[184:185], off
	v_lshl_add_u64 v[184:185], s[14:15], 0, v[144:145]
	s_add_i32 m0, s52, 0x2000
	s_nop 0
	global_load_lds_dwordx4 v[184:185], off
	v_lshl_add_u64 v[184:185], v[218:219], 0, s[82:83]
	s_mov_b32 m0, s71
	s_nop 0
	global_load_lds_dwordx4 v[184:185], off
	v_lshl_add_u64 v[184:185], v[220:221], 0, s[82:83]
	s_mov_b32 m0, s74
	s_nop 0
	global_load_lds_dwordx4 v[184:185], off
	s_waitcnt vmcnt(8)
	s_waitcnt lgkmcnt(0)
	s_barrier
	s_setprio 1
	v_mfma_f32_16x16x32_bf16 v[62:65], v[130:133], v[208:211], v[62:65]
	v_mfma_f32_16x16x32_bf16 v[58:61], v[176:179], v[208:211], v[58:61]
	v_mfma_f32_16x16x32_bf16 v[46:49], v[130:133], v[226:229], v[46:49]
	v_mfma_f32_16x16x32_bf16 v[42:45], v[176:179], v[226:229], v[42:45]
	v_mfma_f32_16x16x32_bf16 v[30:33], v[130:133], v[234:237], v[30:33]
	v_mfma_f32_16x16x32_bf16 v[26:29], v[176:179], v[234:237], v[26:29]
	v_mfma_f32_16x16x32_bf16 v[14:17], v[130:133], v[242:245], v[14:17]
	v_mfma_f32_16x16x32_bf16 v[10:13], v[176:179], v[242:245], v[10:13]
	v_mfma_f32_16x16x32_bf16 v[62:65], v[134:137], v[212:215], v[62:65]
	v_mfma_f32_16x16x32_bf16 v[58:61], v[180:183], v[212:215], v[58:61]
	v_mfma_f32_16x16x32_bf16 v[46:49], v[134:137], v[230:233], v[46:49]
	v_mfma_f32_16x16x32_bf16 v[42:45], v[180:183], v[230:233], v[42:45]
	v_mfma_f32_16x16x32_bf16 v[30:33], v[134:137], v[238:241], v[30:33]
	v_mfma_f32_16x16x32_bf16 v[26:29], v[180:183], v[238:241], v[26:29]
	v_mfma_f32_16x16x32_bf16 v[14:17], v[134:137], v[246:249], v[14:17]
	v_mfma_f32_16x16x32_bf16 v[10:13], v[180:183], v[246:249], v[10:13]
	v_mfma_f32_16x16x32_bf16 v[54:57], v[192:195], v[208:211], v[54:57]
	v_mfma_f32_16x16x32_bf16 v[50:53], v[200:203], v[208:211], v[50:53]
	v_mfma_f32_16x16x32_bf16 v[38:41], v[192:195], v[226:229], v[38:41]
	v_mfma_f32_16x16x32_bf16 v[34:37], v[200:203], v[226:229], v[34:37]
	v_mfma_f32_16x16x32_bf16 v[22:25], v[192:195], v[234:237], v[22:25]
	v_mfma_f32_16x16x32_bf16 v[18:21], v[200:203], v[234:237], v[18:21]
	v_mfma_f32_16x16x32_bf16 v[6:9], v[192:195], v[242:245], v[6:9]
	v_mfma_f32_16x16x32_bf16 v[2:5], v[200:203], v[242:245], v[2:5]
	v_mfma_f32_16x16x32_bf16 v[54:57], v[196:199], v[212:215], v[54:57]
	v_mfma_f32_16x16x32_bf16 v[50:53], v[204:207], v[212:215], v[50:53]
	v_mfma_f32_16x16x32_bf16 v[38:41], v[196:199], v[230:233], v[38:41]
	v_mfma_f32_16x16x32_bf16 v[34:37], v[204:207], v[230:233], v[34:37]
	v_mfma_f32_16x16x32_bf16 v[22:25], v[196:199], v[238:241], v[22:25]
	v_mfma_f32_16x16x32_bf16 v[18:21], v[204:207], v[238:241], v[18:21]
	v_mfma_f32_16x16x32_bf16 v[6:9], v[196:199], v[246:249], v[6:9]
	v_mfma_f32_16x16x32_bf16 v[2:5], v[204:207], v[246:249], v[2:5]
	s_setprio 0
	s_barrier
	s_add_i32 s81, s81, 2
	s_add_u32 s79, s79, 0x100
	s_addc_u32 s80, s80, 0
	s_cmp_gt_u32 s81, 13
	s_cbranch_scc1 .LBB0_222
	s_mov_b64 s[14:15], s[50:51]
	s_branch .LBB0_216

.LBB0_329:
	s_add_u32 s48, s14, 0x100
	s_addc_u32 s49, s15, 0
	s_and_b64 s[50:51], s[50:51], exec
	s_cselect_b32 s53, s56, s49
	s_cselect_b32 s52, s57, s48
	s_cselect_b32 s51, s41, s76
	s_cselect_b32 s50, s71, s75
	s_add_i32 s78, 0, 0x10000
	v_add_u32_e32 v0, s78, v187
	s_add_i32 s79, 0, 0x14000
	ds_read_b128 v[130:133], v0
	ds_read_b128 v[134:137], v0 offset:1024
	ds_read_b128 v[176:179], v0 offset:2048
	ds_read_b128 v[180:183], v0 offset:3072
	v_add_u32_e32 v0, s79, v187
	ds_read_b128 v[192:195], v0
	ds_read_b128 v[196:199], v0 offset:1024
	ds_read_b128 v[200:203], v0 offset:2048
	ds_read_b128 v[204:207], v0 offset:3072
	v_lshl_add_u64 v[184:185], s[14:15], 0, v[172:173]
	s_add_i32 m0, s62, 0xc000
	ds_read_b128 v[208:211], v190
	ds_read_b128 v[212:215], v190 offset:1024
	ds_read_b128 v[226:229], v190 offset:2048
	ds_read_b128 v[230:233], v190 offset:3072
	ds_read_b128 v[234:237], v190 offset:4096
	ds_read_b128 v[238:241], v190 offset:5120
	ds_read_b128 v[242:245], v190 offset:6144
	ds_read_b128 v[246:249], v190 offset:7168
	global_load_lds_dwordx4 v[184:185], off
	v_lshl_add_u64 v[184:185], s[14:15], 0, v[174:175]
	s_add_i32 m0, s62, 0xe000
	s_nop 0
	global_load_lds_dwordx4 v[184:185], off
	s_waitcnt vmcnt(8)
	s_waitcnt lgkmcnt(0)
	s_barrier
	s_setprio 1
	v_mfma_f32_16x16x32_bf16 v[126:129], v[130:133], v[208:211], v[126:129]
	v_mfma_f32_16x16x32_bf16 v[122:125], v[176:179], v[208:211], v[122:125]
	v_mfma_f32_16x16x32_bf16 v[110:113], v[130:133], v[226:229], v[110:113]
	v_mfma_f32_16x16x32_bf16 v[106:109], v[176:179], v[226:229], v[106:109]
	v_mfma_f32_16x16x32_bf16 v[94:97], v[130:133], v[234:237], v[94:97]
	v_mfma_f32_16x16x32_bf16 v[90:93], v[176:179], v[234:237], v[90:93]
	v_mfma_f32_16x16x32_bf16 v[78:81], v[130:133], v[242:245], v[78:81]
	v_mfma_f32_16x16x32_bf16 v[74:77], v[176:179], v[242:245], v[74:77]
	v_mfma_f32_16x16x32_bf16 v[126:129], v[134:137], v[212:215], v[126:129]
	v_mfma_f32_16x16x32_bf16 v[122:125], v[180:183], v[212:215], v[122:125]
	v_mfma_f32_16x16x32_bf16 v[110:113], v[134:137], v[230:233], v[110:113]
	v_mfma_f32_16x16x32_bf16 v[106:109], v[180:183], v[230:233], v[106:109]
	v_mfma_f32_16x16x32_bf16 v[94:97], v[134:137], v[238:241], v[94:97]
	v_mfma_f32_16x16x32_bf16 v[90:93], v[180:183], v[238:241], v[90:93]
	v_mfma_f32_16x16x32_bf16 v[78:81], v[134:137], v[246:249], v[78:81]
	v_mfma_f32_16x16x32_bf16 v[74:77], v[180:183], v[246:249], v[74:77]
	v_mfma_f32_16x16x32_bf16 v[118:121], v[192:195], v[208:211], v[118:121]
	v_mfma_f32_16x16x32_bf16 v[114:117], v[200:203], v[208:211], v[114:117]
	v_mfma_f32_16x16x32_bf16 v[102:105], v[192:195], v[226:229], v[102:105]
	v_mfma_f32_16x16x32_bf16 v[98:101], v[200:203], v[226:229], v[98:101]
	v_mfma_f32_16x16x32_bf16 v[86:89], v[192:195], v[234:237], v[86:89]
	v_mfma_f32_16x16x32_bf16 v[82:85], v[200:203], v[234:237], v[82:85]
	v_mfma_f32_16x16x32_bf16 v[70:73], v[192:195], v[242:245], v[70:73]
	v_mfma_f32_16x16x32_bf16 v[66:69], v[200:203], v[242:245], v[66:69]
	v_mfma_f32_16x16x32_bf16 v[118:121], v[196:199], v[212:215], v[118:121]
	v_mfma_f32_16x16x32_bf16 v[114:117], v[204:207], v[212:215], v[114:117]
	v_mfma_f32_16x16x32_bf16 v[102:105], v[196:199], v[230:233], v[102:105]
	v_mfma_f32_16x16x32_bf16 v[98:101], v[204:207], v[230:233], v[98:101]
	v_mfma_f32_16x16x32_bf16 v[86:89], v[196:199], v[238:241], v[86:89]
	v_mfma_f32_16x16x32_bf16 v[82:85], v[204:207], v[238:241], v[82:85]
	v_mfma_f32_16x16x32_bf16 v[70:73], v[196:199], v[246:249], v[70:73]
	v_mfma_f32_16x16x32_bf16 v[66:69], v[204:207], v[246:249], v[66:69]
	s_setprio 0
	s_barrier
	s_add_i32 s14, s78, s59
	v_lshl_add_u64 v[184:185], s[50:51], 0, v[140:141]
	s_mov_b32 m0, s14
	ds_read_b128 v[208:211], v190 offset:16384
	ds_read_b128 v[212:215], v190 offset:17408
	ds_read_b128 v[226:229], v190 offset:18432
	ds_read_b128 v[230:233], v190 offset:19456
	ds_read_b128 v[234:237], v190 offset:20480
	ds_read_b128 v[238:241], v190 offset:21504
	ds_read_b128 v[242:245], v190 offset:22528
	ds_read_b128 v[246:249], v190 offset:23552
	global_load_lds_dwordx4 v[184:185], off
	s_add_i32 m0, s14, 0x2000
	s_add_u32 s14, s50, 0x40000
	v_lshl_add_u64 v[216:217], s[50:51], 0, v[144:145]
	s_addc_u32 s15, s51, 0
	s_add_i32 s78, s79, s59
	global_load_lds_dwordx4 v[216:217], off
	v_lshl_add_u64 v[250:251], s[14:15], 0, v[140:141]
	s_mov_b32 m0, s78
	v_lshl_add_u64 v[218:219], s[52:53], 0, v[142:143]
	global_load_lds_dwordx4 v[250:251], off
	v_lshl_add_u64 v[250:251], s[14:15], 0, v[144:145]
	s_add_i32 m0, s78, 0x2000
	s_nop 0
	global_load_lds_dwordx4 v[250:251], off
	v_lshl_add_u64 v[250:251], s[52:53], 0, v[138:139]
	s_mov_b32 m0, s62
	s_nop 0
	global_load_lds_dwordx4 v[250:251], off
	s_mov_b32 m0, s63
	s_nop 0
	global_load_lds_dwordx4 v[218:219], off
	s_waitcnt vmcnt(8)
	s_waitcnt lgkmcnt(0)
	s_barrier
	s_setprio 1
	v_mfma_f32_16x16x32_bf16 v[62:65], v[130:133], v[208:211], v[62:65]
	v_mfma_f32_16x16x32_bf16 v[58:61], v[176:179], v[208:211], v[58:61]
	v_mfma_f32_16x16x32_bf16 v[46:49], v[130:133], v[226:229], v[46:49]
	v_mfma_f32_16x16x32_bf16 v[42:45], v[176:179], v[226:229], v[42:45]
	v_mfma_f32_16x16x32_bf16 v[30:33], v[130:133], v[234:237], v[30:33]
	v_mfma_f32_16x16x32_bf16 v[26:29], v[176:179], v[234:237], v[26:29]
	v_mfma_f32_16x16x32_bf16 v[14:17], v[130:133], v[242:245], v[14:17]
	v_mfma_f32_16x16x32_bf16 v[10:13], v[176:179], v[242:245], v[10:13]
	v_mfma_f32_16x16x32_bf16 v[62:65], v[134:137], v[212:215], v[62:65]
	v_mfma_f32_16x16x32_bf16 v[58:61], v[180:183], v[212:215], v[58:61]
	v_mfma_f32_16x16x32_bf16 v[46:49], v[134:137], v[230:233], v[46:49]
	v_mfma_f32_16x16x32_bf16 v[42:45], v[180:183], v[230:233], v[42:45]
	v_mfma_f32_16x16x32_bf16 v[30:33], v[134:137], v[238:241], v[30:33]
	v_mfma_f32_16x16x32_bf16 v[26:29], v[180:183], v[238:241], v[26:29]
	v_mfma_f32_16x16x32_bf16 v[14:17], v[134:137], v[246:249], v[14:17]
	v_mfma_f32_16x16x32_bf16 v[10:13], v[180:183], v[246:249], v[10:13]
	v_mfma_f32_16x16x32_bf16 v[54:57], v[192:195], v[208:211], v[54:57]
	v_mfma_f32_16x16x32_bf16 v[50:53], v[200:203], v[208:211], v[50:53]
	v_mfma_f32_16x16x32_bf16 v[38:41], v[192:195], v[226:229], v[38:41]
	v_mfma_f32_16x16x32_bf16 v[34:37], v[200:203], v[226:229], v[34:37]
	v_mfma_f32_16x16x32_bf16 v[22:25], v[192:195], v[234:237], v[22:25]
	v_mfma_f32_16x16x32_bf16 v[18:21], v[200:203], v[234:237], v[18:21]
	v_mfma_f32_16x16x32_bf16 v[6:9], v[192:195], v[242:245], v[6:9]
	v_mfma_f32_16x16x32_bf16 v[2:5], v[200:203], v[242:245], v[2:5]
	v_mfma_f32_16x16x32_bf16 v[54:57], v[196:199], v[212:215], v[54:57]
	v_mfma_f32_16x16x32_bf16 v[50:53], v[204:207], v[212:215], v[50:53]
	v_mfma_f32_16x16x32_bf16 v[38:41], v[196:199], v[230:233], v[38:41]
	v_mfma_f32_16x16x32_bf16 v[34:37], v[204:207], v[230:233], v[34:37]
	v_mfma_f32_16x16x32_bf16 v[22:25], v[196:199], v[238:241], v[22:25]
	v_mfma_f32_16x16x32_bf16 v[18:21], v[204:207], v[238:241], v[18:21]
	v_mfma_f32_16x16x32_bf16 v[6:9], v[196:199], v[246:249], v[6:9]
	v_mfma_f32_16x16x32_bf16 v[2:5], v[204:207], v[246:249], v[2:5]
	s_setprio 0
	s_barrier
	s_add_i32 s78, 0, 0x18000
	v_add_u32_e32 v0, s78, v187
	s_add_i32 s79, 0, 0x1c000
	ds_read_b128 v[130:133], v0
	ds_read_b128 v[134:137], v0 offset:1024
	ds_read_b128 v[176:179], v0 offset:2048
	ds_read_b128 v[180:183], v0 offset:3072
	v_add_u32_e32 v0, s79, v187
	ds_read_b128 v[192:195], v0
	ds_read_b128 v[196:199], v0 offset:1024
	ds_read_b128 v[200:203], v0 offset:2048
	ds_read_b128 v[204:207], v0 offset:3072
	s_add_u32 s14, s52, 0x40000
	s_addc_u32 s15, s53, 0
	s_mov_b32 m0, s64
	v_lshl_add_u64 v[220:221], s[14:15], 0, v[138:139]
	ds_read_b128 v[208:211], v190 offset:32768
	ds_read_b128 v[212:215], v190 offset:33792
	ds_read_b128 v[226:229], v190 offset:34816
	ds_read_b128 v[230:233], v190 offset:35840
	ds_read_b128 v[234:237], v190 offset:36864
	ds_read_b128 v[238:241], v190 offset:37888
	ds_read_b128 v[242:245], v190 offset:38912
	ds_read_b128 v[246:249], v190 offset:39936
	global_load_lds_dwordx4 v[220:221], off
	v_lshl_add_u64 v[220:221], s[14:15], 0, v[142:143]
	s_mov_b32 m0, s65
	s_nop 0
	global_load_lds_dwordx4 v[220:221], off
	s_waitcnt vmcnt(8)
	s_waitcnt lgkmcnt(0)
	s_barrier
	s_setprio 1
	v_mfma_f32_16x16x32_bf16 v[126:129], v[130:133], v[208:211], v[126:129]
	v_mfma_f32_16x16x32_bf16 v[122:125], v[176:179], v[208:211], v[122:125]
	v_mfma_f32_16x16x32_bf16 v[110:113], v[130:133], v[226:229], v[110:113]
	v_mfma_f32_16x16x32_bf16 v[106:109], v[176:179], v[226:229], v[106:109]
	v_mfma_f32_16x16x32_bf16 v[94:97], v[130:133], v[234:237], v[94:97]
	v_mfma_f32_16x16x32_bf16 v[90:93], v[176:179], v[234:237], v[90:93]
	v_mfma_f32_16x16x32_bf16 v[78:81], v[130:133], v[242:245], v[78:81]
	v_mfma_f32_16x16x32_bf16 v[74:77], v[176:179], v[242:245], v[74:77]
	v_mfma_f32_16x16x32_bf16 v[126:129], v[134:137], v[212:215], v[126:129]
	v_mfma_f32_16x16x32_bf16 v[122:125], v[180:183], v[212:215], v[122:125]
	v_mfma_f32_16x16x32_bf16 v[110:113], v[134:137], v[230:233], v[110:113]
	v_mfma_f32_16x16x32_bf16 v[106:109], v[180:183], v[230:233], v[106:109]
	v_mfma_f32_16x16x32_bf16 v[94:97], v[134:137], v[238:241], v[94:97]
	v_mfma_f32_16x16x32_bf16 v[90:93], v[180:183], v[238:241], v[90:93]
	v_mfma_f32_16x16x32_bf16 v[78:81], v[134:137], v[246:249], v[78:81]
	v_mfma_f32_16x16x32_bf16 v[74:77], v[180:183], v[246:249], v[74:77]
	v_mfma_f32_16x16x32_bf16 v[118:121], v[192:195], v[208:211], v[118:121]
	v_mfma_f32_16x16x32_bf16 v[114:117], v[200:203], v[208:211], v[114:117]
	v_mfma_f32_16x16x32_bf16 v[102:105], v[192:195], v[226:229], v[102:105]
	v_mfma_f32_16x16x32_bf16 v[98:101], v[200:203], v[226:229], v[98:101]
	v_mfma_f32_16x16x32_bf16 v[86:89], v[192:195], v[234:237], v[86:89]
	v_mfma_f32_16x16x32_bf16 v[82:85], v[200:203], v[234:237], v[82:85]
	v_mfma_f32_16x16x32_bf16 v[70:73], v[192:195], v[242:245], v[70:73]
	v_mfma_f32_16x16x32_bf16 v[66:69], v[200:203], v[242:245], v[66:69]
	v_mfma_f32_16x16x32_bf16 v[118:121], v[196:199], v[212:215], v[118:121]
	v_mfma_f32_16x16x32_bf16 v[114:117], v[204:207], v[212:215], v[114:117]
	v_mfma_f32_16x16x32_bf16 v[102:105], v[196:199], v[230:233], v[102:105]
	v_mfma_f32_16x16x32_bf16 v[98:101], v[204:207], v[230:233], v[98:101]
	v_mfma_f32_16x16x32_bf16 v[86:89], v[196:199], v[238:241], v[86:89]
	v_mfma_f32_16x16x32_bf16 v[82:85], v[204:207], v[238:241], v[82:85]
	v_mfma_f32_16x16x32_bf16 v[70:73], v[196:199], v[246:249], v[70:73]
	v_mfma_f32_16x16x32_bf16 v[66:69], v[204:207], v[246:249], v[66:69]
	s_setprio 0
	s_barrier
	s_add_i32 s14, s78, s59
	v_lshl_add_u64 v[184:185], v[184:185], 0, s[82:83]
	s_mov_b32 m0, s14
	ds_read_b128 v[208:211], v190 offset:49152
	ds_read_b128 v[212:215], v190 offset:50176
	ds_read_b128 v[226:229], v190 offset:51200
	ds_read_b128 v[230:233], v190 offset:52224
	ds_read_b128 v[234:237], v190 offset:53248
	ds_read_b128 v[238:241], v190 offset:54272
	ds_read_b128 v[242:245], v190 offset:55296
	ds_read_b128 v[246:249], v190 offset:56320
	global_load_lds_dwordx4 v[184:185], off
	s_add_i32 m0, s14, 0x2000
	s_add_u32 s14, s50, 0x40080
	v_lshl_add_u64 v[184:185], v[216:217], 0, s[82:83]
	s_addc_u32 s15, s51, 0
	s_add_i32 s50, s79, s59
	global_load_lds_dwordx4 v[184:185], off
	v_lshl_add_u64 v[184:185], s[14:15], 0, v[140:141]
	s_mov_b32 m0, s50
	s_nop 0
	global_load_lds_dwordx4 v[184:185], off
	v_lshl_add_u64 v[184:185], s[14:15], 0, v[144:145]
	s_add_i32 m0, s50, 0x2000
	s_nop 0
	global_load_lds_dwordx4 v[184:185], off
	v_lshl_add_u64 v[184:185], v[250:251], 0, s[82:83]
	s_mov_b32 m0, s67
	s_nop 0
	global_load_lds_dwordx4 v[184:185], off
	v_lshl_add_u64 v[184:185], v[218:219], 0, s[82:83]
	s_mov_b32 m0, s68
	s_nop 0
	global_load_lds_dwordx4 v[184:185], off
	s_waitcnt vmcnt(8)
	s_waitcnt lgkmcnt(0)
	s_barrier
	s_setprio 1
	v_mfma_f32_16x16x32_bf16 v[62:65], v[130:133], v[208:211], v[62:65]
	v_mfma_f32_16x16x32_bf16 v[58:61], v[176:179], v[208:211], v[58:61]
	v_mfma_f32_16x16x32_bf16 v[46:49], v[130:133], v[226:229], v[46:49]
	v_mfma_f32_16x16x32_bf16 v[42:45], v[176:179], v[226:229], v[42:45]
	v_mfma_f32_16x16x32_bf16 v[30:33], v[130:133], v[234:237], v[30:33]
	v_mfma_f32_16x16x32_bf16 v[26:29], v[176:179], v[234:237], v[26:29]
	v_mfma_f32_16x16x32_bf16 v[14:17], v[130:133], v[242:245], v[14:17]
	v_mfma_f32_16x16x32_bf16 v[10:13], v[176:179], v[242:245], v[10:13]
	v_mfma_f32_16x16x32_bf16 v[62:65], v[134:137], v[212:215], v[62:65]
	v_mfma_f32_16x16x32_bf16 v[58:61], v[180:183], v[212:215], v[58:61]
	v_mfma_f32_16x16x32_bf16 v[46:49], v[134:137], v[230:233], v[46:49]
	v_mfma_f32_16x16x32_bf16 v[42:45], v[180:183], v[230:233], v[42:45]
	v_mfma_f32_16x16x32_bf16 v[30:33], v[134:137], v[238:241], v[30:33]
	v_mfma_f32_16x16x32_bf16 v[26:29], v[180:183], v[238:241], v[26:29]
	v_mfma_f32_16x16x32_bf16 v[14:17], v[134:137], v[246:249], v[14:17]
	v_mfma_f32_16x16x32_bf16 v[10:13], v[180:183], v[246:249], v[10:13]
	v_mfma_f32_16x16x32_bf16 v[54:57], v[192:195], v[208:211], v[54:57]
	v_mfma_f32_16x16x32_bf16 v[50:53], v[200:203], v[208:211], v[50:53]
	v_mfma_f32_16x16x32_bf16 v[38:41], v[192:195], v[226:229], v[38:41]
	v_mfma_f32_16x16x32_bf16 v[34:37], v[200:203], v[226:229], v[34:37]
	v_mfma_f32_16x16x32_bf16 v[22:25], v[192:195], v[234:237], v[22:25]
	v_mfma_f32_16x16x32_bf16 v[18:21], v[200:203], v[234:237], v[18:21]
	v_mfma_f32_16x16x32_bf16 v[6:9], v[192:195], v[242:245], v[6:9]
	v_mfma_f32_16x16x32_bf16 v[2:5], v[200:203], v[242:245], v[2:5]
	v_mfma_f32_16x16x32_bf16 v[54:57], v[196:199], v[212:215], v[54:57]
	v_mfma_f32_16x16x32_bf16 v[50:53], v[204:207], v[212:215], v[50:53]
	v_mfma_f32_16x16x32_bf16 v[38:41], v[196:199], v[230:233], v[38:41]
	v_mfma_f32_16x16x32_bf16 v[34:37], v[204:207], v[230:233], v[34:37]
	v_mfma_f32_16x16x32_bf16 v[22:25], v[196:199], v[238:241], v[22:25]
	v_mfma_f32_16x16x32_bf16 v[18:21], v[204:207], v[238:241], v[18:21]
	v_mfma_f32_16x16x32_bf16 v[6:9], v[196:199], v[246:249], v[6:9]
	v_mfma_f32_16x16x32_bf16 v[2:5], v[204:207], v[246:249], v[2:5]
	s_setprio 0
	s_barrier
	s_add_i32 s77, s77, 2
	s_add_u32 s75, s75, 0x100
	s_addc_u32 s76, s76, 0
	s_cmp_gt_u32 s77, 13
	s_cbranch_scc1 .LBB0_331
	s_mov_b64 s[14:15], s[48:49]
	s_branch .LBB0_325

.LBB0_443:
	s_add_u32 s22, s4, 0x100
	s_addc_u32 s23, s5, 0
	s_and_b64 s[24:25], s[24:25], exec
	s_cselect_b32 s27, s49, s23
	s_cselect_b32 s26, s50, s22
	s_cselect_b32 s25, s15, s54
	s_cselect_b32 s24, s51, s53
	s_add_i32 s56, 0, 0x10000
	v_add_u32_e32 v0, s56, v173
	s_add_i32 s57, 0, 0x14000
	ds_read_b128 v[178:181], v0
	ds_read_b128 v[182:185], v0 offset:1024
	ds_read_b128 v[186:189], v0 offset:2048
	ds_read_b128 v[190:193], v0 offset:3072
	v_add_u32_e32 v0, s57, v173
	ds_read_b128 v[194:197], v0
	ds_read_b128 v[198:201], v0 offset:1024
	ds_read_b128 v[202:205], v0 offset:2048
	ds_read_b128 v[206:209], v0 offset:3072
	v_lshl_add_u64 v[218:219], s[4:5], 0, v[138:139]
	s_add_i32 m0, s36, 0xc000
	ds_read_b128 v[210:213], v177
	ds_read_b128 v[214:217], v177 offset:1024
	ds_read_b128 v[226:229], v177 offset:2048
	ds_read_b128 v[230:233], v177 offset:3072
	ds_read_b128 v[234:237], v177 offset:4096
	ds_read_b128 v[238:241], v177 offset:5120
	ds_read_b128 v[242:245], v177 offset:6144
	ds_read_b128 v[246:249], v177 offset:7168
	global_load_lds_dwordx4 v[218:219], off
	v_lshl_add_u64 v[218:219], s[4:5], 0, v[140:141]
	s_add_i32 m0, s36, 0xe000
	s_nop 0
	global_load_lds_dwordx4 v[218:219], off
	s_waitcnt vmcnt(8)
	s_waitcnt lgkmcnt(0)
	s_barrier
	s_setprio 1
	v_mfma_f32_16x16x32_bf16 v[126:129], v[178:181], v[210:213], v[126:129]
	v_mfma_f32_16x16x32_bf16 v[122:125], v[186:189], v[210:213], v[122:125]
	v_mfma_f32_16x16x32_bf16 v[110:113], v[178:181], v[226:229], v[110:113]
	v_mfma_f32_16x16x32_bf16 v[106:109], v[186:189], v[226:229], v[106:109]
	v_mfma_f32_16x16x32_bf16 v[94:97], v[178:181], v[234:237], v[94:97]
	v_mfma_f32_16x16x32_bf16 v[90:93], v[186:189], v[234:237], v[90:93]
	v_mfma_f32_16x16x32_bf16 v[78:81], v[178:181], v[242:245], v[78:81]
	v_mfma_f32_16x16x32_bf16 v[74:77], v[186:189], v[242:245], v[74:77]
	v_mfma_f32_16x16x32_bf16 v[126:129], v[182:185], v[214:217], v[126:129]
	v_mfma_f32_16x16x32_bf16 v[122:125], v[190:193], v[214:217], v[122:125]
	v_mfma_f32_16x16x32_bf16 v[110:113], v[182:185], v[230:233], v[110:113]
	v_mfma_f32_16x16x32_bf16 v[106:109], v[190:193], v[230:233], v[106:109]
	v_mfma_f32_16x16x32_bf16 v[94:97], v[182:185], v[238:241], v[94:97]
	v_mfma_f32_16x16x32_bf16 v[90:93], v[190:193], v[238:241], v[90:93]
	v_mfma_f32_16x16x32_bf16 v[78:81], v[182:185], v[246:249], v[78:81]
	v_mfma_f32_16x16x32_bf16 v[74:77], v[190:193], v[246:249], v[74:77]
	v_mfma_f32_16x16x32_bf16 v[118:121], v[194:197], v[210:213], v[118:121]
	v_mfma_f32_16x16x32_bf16 v[114:117], v[202:205], v[210:213], v[114:117]
	v_mfma_f32_16x16x32_bf16 v[102:105], v[194:197], v[226:229], v[102:105]
	v_mfma_f32_16x16x32_bf16 v[98:101], v[202:205], v[226:229], v[98:101]
	v_mfma_f32_16x16x32_bf16 v[86:89], v[194:197], v[234:237], v[86:89]
	v_mfma_f32_16x16x32_bf16 v[82:85], v[202:205], v[234:237], v[82:85]
	v_mfma_f32_16x16x32_bf16 v[70:73], v[194:197], v[242:245], v[70:73]
	v_mfma_f32_16x16x32_bf16 v[66:69], v[202:205], v[242:245], v[66:69]
	v_mfma_f32_16x16x32_bf16 v[118:121], v[198:201], v[214:217], v[118:121]
	v_mfma_f32_16x16x32_bf16 v[114:117], v[206:209], v[214:217], v[114:117]
	v_mfma_f32_16x16x32_bf16 v[102:105], v[198:201], v[230:233], v[102:105]
	v_mfma_f32_16x16x32_bf16 v[98:101], v[206:209], v[230:233], v[98:101]
	v_mfma_f32_16x16x32_bf16 v[86:89], v[198:201], v[238:241], v[86:89]
	v_mfma_f32_16x16x32_bf16 v[82:85], v[206:209], v[238:241], v[82:85]
	v_mfma_f32_16x16x32_bf16 v[70:73], v[198:201], v[246:249], v[70:73]
	v_mfma_f32_16x16x32_bf16 v[66:69], v[206:209], v[246:249], v[66:69]
	s_setprio 0
	s_barrier
	s_add_i32 s4, s56, s35
	v_lshl_add_u64 v[218:219], s[24:25], 0, v[132:133]
	s_mov_b32 m0, s4
	ds_read_b128 v[210:213], v177 offset:16384
	ds_read_b128 v[214:217], v177 offset:17408
	ds_read_b128 v[226:229], v177 offset:18432
	ds_read_b128 v[230:233], v177 offset:19456
	ds_read_b128 v[234:237], v177 offset:20480
	ds_read_b128 v[238:241], v177 offset:21504
	ds_read_b128 v[242:245], v177 offset:22528
	ds_read_b128 v[246:249], v177 offset:23552
	global_load_lds_dwordx4 v[218:219], off
	s_add_i32 m0, s4, 0x2000
	s_add_u32 s4, s24, 0x40000
	v_lshl_add_u64 v[220:221], s[24:25], 0, v[136:137]
	s_addc_u32 s5, s25, 0
	s_add_i32 s56, s57, s35
	global_load_lds_dwordx4 v[220:221], off
	v_lshl_add_u64 v[250:251], s[4:5], 0, v[132:133]
	s_mov_b32 m0, s56
	v_lshl_add_u64 v[162:163], s[26:27], 0, v[134:135]
	global_load_lds_dwordx4 v[250:251], off
	v_lshl_add_u64 v[250:251], s[4:5], 0, v[136:137]
	s_add_i32 m0, s56, 0x2000
	s_nop 0
	global_load_lds_dwordx4 v[250:251], off
	v_lshl_add_u64 v[250:251], s[26:27], 0, v[130:131]
	s_mov_b32 m0, s36
	s_nop 0
	global_load_lds_dwordx4 v[250:251], off
	s_mov_b32 m0, s37
	s_nop 0
	global_load_lds_dwordx4 v[162:163], off
	s_waitcnt vmcnt(8)
	s_waitcnt lgkmcnt(0)
	s_barrier
	s_setprio 1
	v_mfma_f32_16x16x32_bf16 v[62:65], v[178:181], v[210:213], v[62:65]
	v_mfma_f32_16x16x32_bf16 v[58:61], v[186:189], v[210:213], v[58:61]
	v_mfma_f32_16x16x32_bf16 v[50:53], v[178:181], v[226:229], v[50:53]
	v_mfma_f32_16x16x32_bf16 v[42:45], v[186:189], v[226:229], v[42:45]
	v_mfma_f32_16x16x32_bf16 v[34:37], v[178:181], v[234:237], v[34:37]
	v_mfma_f32_16x16x32_bf16 v[26:29], v[186:189], v[234:237], v[26:29]
	v_mfma_f32_16x16x32_bf16 v[18:21], v[178:181], v[242:245], v[18:21]
	v_mfma_f32_16x16x32_bf16 v[10:13], v[186:189], v[242:245], v[10:13]
	v_mfma_f32_16x16x32_bf16 v[62:65], v[182:185], v[214:217], v[62:65]
	v_mfma_f32_16x16x32_bf16 v[58:61], v[190:193], v[214:217], v[58:61]
	v_mfma_f32_16x16x32_bf16 v[50:53], v[182:185], v[230:233], v[50:53]
	v_mfma_f32_16x16x32_bf16 v[42:45], v[190:193], v[230:233], v[42:45]
	v_mfma_f32_16x16x32_bf16 v[34:37], v[182:185], v[238:241], v[34:37]
	v_mfma_f32_16x16x32_bf16 v[26:29], v[190:193], v[238:241], v[26:29]
	v_mfma_f32_16x16x32_bf16 v[18:21], v[182:185], v[246:249], v[18:21]
	v_mfma_f32_16x16x32_bf16 v[10:13], v[190:193], v[246:249], v[10:13]
	v_mfma_f32_16x16x32_bf16 v[54:57], v[194:197], v[210:213], v[54:57]
	v_mfma_f32_16x16x32_bf16 v[46:49], v[202:205], v[210:213], v[46:49]
	v_mfma_f32_16x16x32_bf16 v[38:41], v[194:197], v[226:229], v[38:41]
	v_mfma_f32_16x16x32_bf16 v[30:33], v[202:205], v[226:229], v[30:33]
	v_mfma_f32_16x16x32_bf16 v[22:25], v[194:197], v[234:237], v[22:25]
	v_mfma_f32_16x16x32_bf16 v[14:17], v[202:205], v[234:237], v[14:17]
	v_mfma_f32_16x16x32_bf16 v[6:9], v[194:197], v[242:245], v[6:9]
	v_mfma_f32_16x16x32_bf16 v[2:5], v[202:205], v[242:245], v[2:5]
	v_mfma_f32_16x16x32_bf16 v[54:57], v[198:201], v[214:217], v[54:57]
	v_mfma_f32_16x16x32_bf16 v[46:49], v[206:209], v[214:217], v[46:49]
	v_mfma_f32_16x16x32_bf16 v[38:41], v[198:201], v[230:233], v[38:41]
	v_mfma_f32_16x16x32_bf16 v[30:33], v[206:209], v[230:233], v[30:33]
	v_mfma_f32_16x16x32_bf16 v[22:25], v[198:201], v[238:241], v[22:25]
	v_mfma_f32_16x16x32_bf16 v[14:17], v[206:209], v[238:241], v[14:17]
	v_mfma_f32_16x16x32_bf16 v[6:9], v[198:201], v[246:249], v[6:9]
	v_mfma_f32_16x16x32_bf16 v[2:5], v[206:209], v[246:249], v[2:5]
	s_setprio 0
	s_barrier
	s_add_i32 s56, 0, 0x18000
	v_add_u32_e32 v0, s56, v173
	s_add_i32 s57, 0, 0x1c000
	ds_read_b128 v[178:181], v0
	ds_read_b128 v[182:185], v0 offset:1024
	ds_read_b128 v[186:189], v0 offset:2048
	ds_read_b128 v[190:193], v0 offset:3072
	v_add_u32_e32 v0, s57, v173
	ds_read_b128 v[194:197], v0
	ds_read_b128 v[198:201], v0 offset:1024
	ds_read_b128 v[202:205], v0 offset:2048
	ds_read_b128 v[206:209], v0 offset:3072
	s_add_u32 s4, s26, 0x40000
	s_addc_u32 s5, s27, 0
	s_mov_b32 m0, s38
	v_lshl_add_u64 v[158:159], s[4:5], 0, v[130:131]
	ds_read_b128 v[210:213], v177 offset:32768
	ds_read_b128 v[214:217], v177 offset:33792
	ds_read_b128 v[226:229], v177 offset:34816
	ds_read_b128 v[230:233], v177 offset:35840
	ds_read_b128 v[234:237], v177 offset:36864
	ds_read_b128 v[238:241], v177 offset:37888
	ds_read_b128 v[242:245], v177 offset:38912
	ds_read_b128 v[246:249], v177 offset:39936
	global_load_lds_dwordx4 v[158:159], off
	v_lshl_add_u64 v[158:159], s[4:5], 0, v[134:135]
	s_mov_b32 m0, s39
	s_nop 0
	global_load_lds_dwordx4 v[158:159], off
	s_waitcnt vmcnt(8)
	s_waitcnt lgkmcnt(0)
	s_barrier
	s_setprio 1
	v_mfma_f32_16x16x32_bf16 v[126:129], v[178:181], v[210:213], v[126:129]
	v_mfma_f32_16x16x32_bf16 v[122:125], v[186:189], v[210:213], v[122:125]
	v_mfma_f32_16x16x32_bf16 v[110:113], v[178:181], v[226:229], v[110:113]
	v_mfma_f32_16x16x32_bf16 v[106:109], v[186:189], v[226:229], v[106:109]
	v_mfma_f32_16x16x32_bf16 v[94:97], v[178:181], v[234:237], v[94:97]
	v_mfma_f32_16x16x32_bf16 v[90:93], v[186:189], v[234:237], v[90:93]
	v_mfma_f32_16x16x32_bf16 v[78:81], v[178:181], v[242:245], v[78:81]
	v_mfma_f32_16x16x32_bf16 v[74:77], v[186:189], v[242:245], v[74:77]
	v_mfma_f32_16x16x32_bf16 v[126:129], v[182:185], v[214:217], v[126:129]
	v_mfma_f32_16x16x32_bf16 v[122:125], v[190:193], v[214:217], v[122:125]
	v_mfma_f32_16x16x32_bf16 v[110:113], v[182:185], v[230:233], v[110:113]
	v_mfma_f32_16x16x32_bf16 v[106:109], v[190:193], v[230:233], v[106:109]
	v_mfma_f32_16x16x32_bf16 v[94:97], v[182:185], v[238:241], v[94:97]
	v_mfma_f32_16x16x32_bf16 v[90:93], v[190:193], v[238:241], v[90:93]
	v_mfma_f32_16x16x32_bf16 v[78:81], v[182:185], v[246:249], v[78:81]
	v_mfma_f32_16x16x32_bf16 v[74:77], v[190:193], v[246:249], v[74:77]
	v_mfma_f32_16x16x32_bf16 v[118:121], v[194:197], v[210:213], v[118:121]
	v_mfma_f32_16x16x32_bf16 v[114:117], v[202:205], v[210:213], v[114:117]
	v_mfma_f32_16x16x32_bf16 v[102:105], v[194:197], v[226:229], v[102:105]
	v_mfma_f32_16x16x32_bf16 v[98:101], v[202:205], v[226:229], v[98:101]
	v_mfma_f32_16x16x32_bf16 v[86:89], v[194:197], v[234:237], v[86:89]
	v_mfma_f32_16x16x32_bf16 v[82:85], v[202:205], v[234:237], v[82:85]
	v_mfma_f32_16x16x32_bf16 v[70:73], v[194:197], v[242:245], v[70:73]
	v_mfma_f32_16x16x32_bf16 v[66:69], v[202:205], v[242:245], v[66:69]
	v_mfma_f32_16x16x32_bf16 v[118:121], v[198:201], v[214:217], v[118:121]
	v_mfma_f32_16x16x32_bf16 v[114:117], v[206:209], v[214:217], v[114:117]
	v_mfma_f32_16x16x32_bf16 v[102:105], v[198:201], v[230:233], v[102:105]
	v_mfma_f32_16x16x32_bf16 v[98:101], v[206:209], v[230:233], v[98:101]
	v_mfma_f32_16x16x32_bf16 v[86:89], v[198:201], v[238:241], v[86:89]
	v_mfma_f32_16x16x32_bf16 v[82:85], v[206:209], v[238:241], v[82:85]
	v_mfma_f32_16x16x32_bf16 v[70:73], v[198:201], v[246:249], v[70:73]
	v_mfma_f32_16x16x32_bf16 v[66:69], v[206:209], v[246:249], v[66:69]
	s_setprio 0
	s_barrier
	s_add_i32 s4, s56, s35
	v_lshl_add_u64 v[158:159], v[218:219], 0, s[82:83]
	s_mov_b32 m0, s4
	ds_read_b128 v[210:213], v177 offset:49152
	ds_read_b128 v[214:217], v177 offset:50176
	ds_read_b128 v[226:229], v177 offset:51200
	ds_read_b128 v[230:233], v177 offset:52224
	ds_read_b128 v[234:237], v177 offset:53248
	ds_read_b128 v[238:241], v177 offset:54272
	ds_read_b128 v[242:245], v177 offset:55296
	ds_read_b128 v[246:249], v177 offset:56320
	global_load_lds_dwordx4 v[158:159], off
	s_add_i32 m0, s4, 0x2000
	s_add_u32 s4, s24, 0x40080
	v_lshl_add_u64 v[158:159], v[220:221], 0, s[82:83]
	s_addc_u32 s5, s25, 0
	s_add_i32 s24, s57, s35
	global_load_lds_dwordx4 v[158:159], off
	v_lshl_add_u64 v[158:159], s[4:5], 0, v[132:133]
	s_mov_b32 m0, s24
	s_nop 0
	global_load_lds_dwordx4 v[158:159], off
	v_lshl_add_u64 v[158:159], s[4:5], 0, v[136:137]
	s_add_i32 m0, s24, 0x2000
	s_nop 0
	global_load_lds_dwordx4 v[158:159], off
	v_lshl_add_u64 v[158:159], v[250:251], 0, s[82:83]
	s_mov_b32 m0, s41
	s_nop 0
	global_load_lds_dwordx4 v[158:159], off
	v_lshl_add_u64 v[158:159], v[162:163], 0, s[82:83]
	s_mov_b32 m0, s42
	s_nop 0
	global_load_lds_dwordx4 v[158:159], off
	s_waitcnt vmcnt(8)
	s_waitcnt lgkmcnt(0)
	s_barrier
	s_setprio 1
	v_mfma_f32_16x16x32_bf16 v[62:65], v[178:181], v[210:213], v[62:65]
	v_mfma_f32_16x16x32_bf16 v[58:61], v[186:189], v[210:213], v[58:61]
	v_mfma_f32_16x16x32_bf16 v[50:53], v[178:181], v[226:229], v[50:53]
	v_mfma_f32_16x16x32_bf16 v[42:45], v[186:189], v[226:229], v[42:45]
	v_mfma_f32_16x16x32_bf16 v[34:37], v[178:181], v[234:237], v[34:37]
	v_mfma_f32_16x16x32_bf16 v[26:29], v[186:189], v[234:237], v[26:29]
	v_mfma_f32_16x16x32_bf16 v[18:21], v[178:181], v[242:245], v[18:21]
	v_mfma_f32_16x16x32_bf16 v[10:13], v[186:189], v[242:245], v[10:13]
	v_mfma_f32_16x16x32_bf16 v[62:65], v[182:185], v[214:217], v[62:65]
	v_mfma_f32_16x16x32_bf16 v[58:61], v[190:193], v[214:217], v[58:61]
	v_mfma_f32_16x16x32_bf16 v[50:53], v[182:185], v[230:233], v[50:53]
	v_mfma_f32_16x16x32_bf16 v[42:45], v[190:193], v[230:233], v[42:45]
	v_mfma_f32_16x16x32_bf16 v[34:37], v[182:185], v[238:241], v[34:37]
	v_mfma_f32_16x16x32_bf16 v[26:29], v[190:193], v[238:241], v[26:29]
	v_mfma_f32_16x16x32_bf16 v[18:21], v[182:185], v[246:249], v[18:21]
	v_mfma_f32_16x16x32_bf16 v[10:13], v[190:193], v[246:249], v[10:13]
	v_mfma_f32_16x16x32_bf16 v[54:57], v[194:197], v[210:213], v[54:57]
	v_mfma_f32_16x16x32_bf16 v[46:49], v[202:205], v[210:213], v[46:49]
	v_mfma_f32_16x16x32_bf16 v[38:41], v[194:197], v[226:229], v[38:41]
	v_mfma_f32_16x16x32_bf16 v[30:33], v[202:205], v[226:229], v[30:33]
	v_mfma_f32_16x16x32_bf16 v[22:25], v[194:197], v[234:237], v[22:25]
	v_mfma_f32_16x16x32_bf16 v[14:17], v[202:205], v[234:237], v[14:17]
	v_mfma_f32_16x16x32_bf16 v[6:9], v[194:197], v[242:245], v[6:9]
	v_mfma_f32_16x16x32_bf16 v[2:5], v[202:205], v[242:245], v[2:5]
	v_mfma_f32_16x16x32_bf16 v[54:57], v[198:201], v[214:217], v[54:57]
	v_mfma_f32_16x16x32_bf16 v[46:49], v[206:209], v[214:217], v[46:49]
	v_mfma_f32_16x16x32_bf16 v[38:41], v[198:201], v[230:233], v[38:41]
	v_mfma_f32_16x16x32_bf16 v[30:33], v[206:209], v[230:233], v[30:33]
	v_mfma_f32_16x16x32_bf16 v[22:25], v[198:201], v[238:241], v[22:25]
	v_mfma_f32_16x16x32_bf16 v[14:17], v[206:209], v[238:241], v[14:17]
	v_mfma_f32_16x16x32_bf16 v[6:9], v[198:201], v[246:249], v[6:9]
	v_mfma_f32_16x16x32_bf16 v[2:5], v[206:209], v[246:249], v[2:5]
	s_setprio 0
	s_barrier
	s_add_i32 s55, s55, 2
	s_add_u32 s53, s53, 0x100
	s_addc_u32 s54, s54, 0
	s_cmp_gt_u32 s55, 13
	s_cbranch_scc1 .LBB0_445
	s_mov_b64 s[4:5], s[22:23]
	s_branch .LBB0_439

.LBB0_693:
	s_add_u32 s24, s22, 0xfffc0080
	s_addc_u32 s25, s23, -1
	s_add_i32 s48, 0, 0x10000
	s_cmp_eq_u32 s47, 12
	s_cselect_b32 s27, s17, s25
	s_cselect_b32 s26, s43, s24
	s_cselect_b32 s25, s15, s46
	s_cselect_b32 s24, s44, s45
	s_add_i32 s50, 0, 0x14000
	v_add_u32_e32 v134, s48, v191
	v_add_u32_e32 v158, s50, v191
	ds_read_b128 v[114:117], v134
	ds_read_b128 v[118:121], v134 offset:1024
	ds_read_b128 v[122:125], v134 offset:2048
	ds_read_b128 v[134:137], v134 offset:3072
	ds_read_b128 v[146:149], v158
	ds_read_b128 v[150:153], v158 offset:1024
	ds_read_b128 v[172:175], v158 offset:2048
	ds_read_b128 v[176:179], v158 offset:3072
	v_lshl_add_u64 v[158:159], s[22:23], 0, v[168:169]
	s_add_i32 m0, s34, 0xc000
	ds_read_b128 v[180:183], v193
	ds_read_b128 v[184:187], v193 offset:1024
	ds_read_b128 v[194:197], v193 offset:2048
	ds_read_b128 v[198:201], v193 offset:3072
	ds_read_b128 v[202:205], v193 offset:4096
	ds_read_b128 v[206:209], v193 offset:5120
	ds_read_b128 v[210:213], v193 offset:6144
	ds_read_b128 v[214:217], v193 offset:7168
	global_load_lds_dwordx4 v[158:159], off
	v_lshl_add_u64 v[158:159], s[22:23], 0, v[170:171]
	s_add_i32 m0, s34, 0xe000
	s_nop 0
	global_load_lds_dwordx4 v[158:159], off
	s_waitcnt vmcnt(8)
	s_waitcnt lgkmcnt(0)
	s_barrier
	s_setprio 1
	v_mfma_f32_16x16x32_bf16 v[142:145], v[114:117], v[180:183], v[142:145]
	v_mfma_f32_16x16x32_bf16 v[138:141], v[122:125], v[180:183], v[138:141]
	v_mfma_f32_16x16x32_bf16 v[110:113], v[114:117], v[194:197], v[110:113]
	v_mfma_f32_16x16x32_bf16 v[106:109], v[122:125], v[194:197], v[106:109]
	v_mfma_f32_16x16x32_bf16 v[94:97], v[114:117], v[202:205], v[94:97]
	v_mfma_f32_16x16x32_bf16 v[90:93], v[122:125], v[202:205], v[90:93]
	v_mfma_f32_16x16x32_bf16 v[78:81], v[114:117], v[210:213], v[78:81]
	v_mfma_f32_16x16x32_bf16 v[74:77], v[122:125], v[210:213], v[74:77]
	v_mfma_f32_16x16x32_bf16 v[142:145], v[118:121], v[184:187], v[142:145]
	v_mfma_f32_16x16x32_bf16 v[138:141], v[134:137], v[184:187], v[138:141]
	v_mfma_f32_16x16x32_bf16 v[110:113], v[118:121], v[198:201], v[110:113]
	v_mfma_f32_16x16x32_bf16 v[106:109], v[134:137], v[198:201], v[106:109]
	v_mfma_f32_16x16x32_bf16 v[94:97], v[118:121], v[206:209], v[94:97]
	v_mfma_f32_16x16x32_bf16 v[90:93], v[134:137], v[206:209], v[90:93]
	v_mfma_f32_16x16x32_bf16 v[78:81], v[118:121], v[214:217], v[78:81]
	v_mfma_f32_16x16x32_bf16 v[74:77], v[134:137], v[214:217], v[74:77]
	v_mfma_f32_16x16x32_bf16 v[130:133], v[146:149], v[180:183], v[130:133]
	v_mfma_f32_16x16x32_bf16 v[126:129], v[172:175], v[180:183], v[126:129]
	v_mfma_f32_16x16x32_bf16 v[102:105], v[146:149], v[194:197], v[102:105]
	v_mfma_f32_16x16x32_bf16 v[98:101], v[172:175], v[194:197], v[98:101]
	v_mfma_f32_16x16x32_bf16 v[86:89], v[146:149], v[202:205], v[86:89]
	v_mfma_f32_16x16x32_bf16 v[82:85], v[172:175], v[202:205], v[82:85]
	v_mfma_f32_16x16x32_bf16 v[70:73], v[146:149], v[210:213], v[70:73]
	v_mfma_f32_16x16x32_bf16 v[66:69], v[172:175], v[210:213], v[66:69]
	v_mfma_f32_16x16x32_bf16 v[130:133], v[150:153], v[184:187], v[130:133]
	v_mfma_f32_16x16x32_bf16 v[126:129], v[176:179], v[184:187], v[126:129]
	v_mfma_f32_16x16x32_bf16 v[102:105], v[150:153], v[198:201], v[102:105]
	v_mfma_f32_16x16x32_bf16 v[98:101], v[176:179], v[198:201], v[98:101]
	v_mfma_f32_16x16x32_bf16 v[86:89], v[150:153], v[206:209], v[86:89]
	v_mfma_f32_16x16x32_bf16 v[82:85], v[176:179], v[206:209], v[82:85]
	v_mfma_f32_16x16x32_bf16 v[70:73], v[150:153], v[214:217], v[70:73]
	v_mfma_f32_16x16x32_bf16 v[66:69], v[176:179], v[214:217], v[66:69]
	s_setprio 0
	s_barrier
	s_add_i32 s48, s48, s33
	v_lshl_add_u64 v[158:159], s[24:25], 0, v[0:1]
	s_mov_b32 m0, s48
	ds_read_b128 v[180:183], v193 offset:16384
	ds_read_b128 v[184:187], v193 offset:17408
	ds_read_b128 v[194:197], v193 offset:18432
	ds_read_b128 v[198:201], v193 offset:19456
	ds_read_b128 v[202:205], v193 offset:20480
	ds_read_b128 v[206:209], v193 offset:21504
	ds_read_b128 v[210:213], v193 offset:22528
	ds_read_b128 v[214:217], v193 offset:23552
	global_load_lds_dwordx4 v[158:159], off
	s_add_i32 m0, s48, 0x2000
	s_add_u32 s48, s24, 0x40000
	v_lshl_add_u64 v[162:163], s[24:25], 0, v[154:155]
	s_addc_u32 s49, s25, 0
	s_add_i32 s50, s50, s33
	global_load_lds_dwordx4 v[162:163], off
	v_lshl_add_u64 v[188:189], s[48:49], 0, v[0:1]
	s_mov_b32 m0, s50
	v_lshl_add_u64 v[218:219], s[26:27], 0, v[156:157]
	global_load_lds_dwordx4 v[188:189], off
	v_lshl_add_u64 v[188:189], s[48:49], 0, v[154:155]
	s_add_i32 m0, s50, 0x2000
	s_nop 0
	global_load_lds_dwordx4 v[188:189], off
	v_lshl_add_u64 v[188:189], s[26:27], 0, v[166:167]
	s_mov_b32 m0, s34
	s_nop 0
	global_load_lds_dwordx4 v[188:189], off
	s_mov_b32 m0, s35
	s_nop 0
	global_load_lds_dwordx4 v[218:219], off
	s_waitcnt vmcnt(8)
	s_waitcnt lgkmcnt(0)
	s_barrier
	s_setprio 1
	v_mfma_f32_16x16x32_bf16 v[62:65], v[114:117], v[180:183], v[62:65]
	v_mfma_f32_16x16x32_bf16 v[58:61], v[122:125], v[180:183], v[58:61]
	v_mfma_f32_16x16x32_bf16 v[46:49], v[114:117], v[194:197], v[46:49]
	v_mfma_f32_16x16x32_bf16 v[42:45], v[122:125], v[194:197], v[42:45]
	v_mfma_f32_16x16x32_bf16 v[30:33], v[114:117], v[202:205], v[30:33]
	v_mfma_f32_16x16x32_bf16 v[26:29], v[122:125], v[202:205], v[26:29]
	v_mfma_f32_16x16x32_bf16 v[14:17], v[114:117], v[210:213], v[14:17]
	v_mfma_f32_16x16x32_bf16 v[10:13], v[122:125], v[210:213], v[10:13]
	v_mfma_f32_16x16x32_bf16 v[62:65], v[118:121], v[184:187], v[62:65]
	v_mfma_f32_16x16x32_bf16 v[58:61], v[134:137], v[184:187], v[58:61]
	v_mfma_f32_16x16x32_bf16 v[46:49], v[118:121], v[198:201], v[46:49]
	v_mfma_f32_16x16x32_bf16 v[42:45], v[134:137], v[198:201], v[42:45]
	v_mfma_f32_16x16x32_bf16 v[30:33], v[118:121], v[206:209], v[30:33]
	v_mfma_f32_16x16x32_bf16 v[26:29], v[134:137], v[206:209], v[26:29]
	v_mfma_f32_16x16x32_bf16 v[14:17], v[118:121], v[214:217], v[14:17]
	v_mfma_f32_16x16x32_bf16 v[10:13], v[134:137], v[214:217], v[10:13]
	v_mfma_f32_16x16x32_bf16 v[54:57], v[146:149], v[180:183], v[54:57]
	v_mfma_f32_16x16x32_bf16 v[50:53], v[172:175], v[180:183], v[50:53]
	v_mfma_f32_16x16x32_bf16 v[38:41], v[146:149], v[194:197], v[38:41]
	v_mfma_f32_16x16x32_bf16 v[34:37], v[172:175], v[194:197], v[34:37]
	v_mfma_f32_16x16x32_bf16 v[22:25], v[146:149], v[202:205], v[22:25]
	v_mfma_f32_16x16x32_bf16 v[18:21], v[172:175], v[202:205], v[18:21]
	v_mfma_f32_16x16x32_bf16 v[6:9], v[146:149], v[210:213], v[6:9]
	v_mfma_f32_16x16x32_bf16 v[2:5], v[172:175], v[210:213], v[2:5]
	v_mfma_f32_16x16x32_bf16 v[54:57], v[150:153], v[184:187], v[54:57]
	v_mfma_f32_16x16x32_bf16 v[50:53], v[176:179], v[184:187], v[50:53]
	v_mfma_f32_16x16x32_bf16 v[38:41], v[150:153], v[198:201], v[38:41]
	v_mfma_f32_16x16x32_bf16 v[34:37], v[176:179], v[198:201], v[34:37]
	v_mfma_f32_16x16x32_bf16 v[22:25], v[150:153], v[206:209], v[22:25]
	v_mfma_f32_16x16x32_bf16 v[18:21], v[176:179], v[206:209], v[18:21]
	v_mfma_f32_16x16x32_bf16 v[6:9], v[150:153], v[214:217], v[6:9]
	v_mfma_f32_16x16x32_bf16 v[2:5], v[176:179], v[214:217], v[2:5]
	s_setprio 0
	s_barrier
	s_add_i32 s48, 0, 0x18000
	s_add_i32 s49, 0, 0x1c000
	v_add_u32_e32 v134, s48, v191
	v_add_u32_e32 v176, s49, v191
	ds_read_b128 v[114:117], v134
	ds_read_b128 v[118:121], v134 offset:1024
	ds_read_b128 v[122:125], v134 offset:2048
	ds_read_b128 v[134:137], v134 offset:3072
	ds_read_b128 v[146:149], v176
	ds_read_b128 v[150:153], v176 offset:1024
	ds_read_b128 v[172:175], v176 offset:2048
	ds_read_b128 v[176:179], v176 offset:3072
	s_add_u32 s26, s26, 0x40000
	s_addc_u32 s27, s27, 0
	s_mov_b32 m0, s36
	v_lshl_add_u64 v[220:221], s[26:27], 0, v[166:167]
	ds_read_b128 v[180:183], v193 offset:32768
	ds_read_b128 v[184:187], v193 offset:33792
	ds_read_b128 v[194:197], v193 offset:34816
	ds_read_b128 v[198:201], v193 offset:35840
	ds_read_b128 v[202:205], v193 offset:36864
	ds_read_b128 v[206:209], v193 offset:37888
	ds_read_b128 v[210:213], v193 offset:38912
	ds_read_b128 v[214:217], v193 offset:39936
	global_load_lds_dwordx4 v[220:221], off
	v_lshl_add_u64 v[220:221], s[26:27], 0, v[156:157]
	s_mov_b32 m0, s37
	s_nop 0
	global_load_lds_dwordx4 v[220:221], off
	s_waitcnt vmcnt(8)
	s_waitcnt lgkmcnt(0)
	s_barrier
	s_setprio 1
	v_mfma_f32_16x16x32_bf16 v[142:145], v[114:117], v[180:183], v[142:145]
	v_mfma_f32_16x16x32_bf16 v[138:141], v[122:125], v[180:183], v[138:141]
	v_mfma_f32_16x16x32_bf16 v[110:113], v[114:117], v[194:197], v[110:113]
	v_mfma_f32_16x16x32_bf16 v[106:109], v[122:125], v[194:197], v[106:109]
	v_mfma_f32_16x16x32_bf16 v[94:97], v[114:117], v[202:205], v[94:97]
	v_mfma_f32_16x16x32_bf16 v[90:93], v[122:125], v[202:205], v[90:93]
	v_mfma_f32_16x16x32_bf16 v[78:81], v[114:117], v[210:213], v[78:81]
	v_mfma_f32_16x16x32_bf16 v[74:77], v[122:125], v[210:213], v[74:77]
	v_mfma_f32_16x16x32_bf16 v[142:145], v[118:121], v[184:187], v[142:145]
	v_mfma_f32_16x16x32_bf16 v[138:141], v[134:137], v[184:187], v[138:141]
	v_mfma_f32_16x16x32_bf16 v[110:113], v[118:121], v[198:201], v[110:113]
	v_mfma_f32_16x16x32_bf16 v[106:109], v[134:137], v[198:201], v[106:109]
	v_mfma_f32_16x16x32_bf16 v[94:97], v[118:121], v[206:209], v[94:97]
	v_mfma_f32_16x16x32_bf16 v[90:93], v[134:137], v[206:209], v[90:93]
	v_mfma_f32_16x16x32_bf16 v[78:81], v[118:121], v[214:217], v[78:81]
	v_mfma_f32_16x16x32_bf16 v[74:77], v[134:137], v[214:217], v[74:77]
	v_mfma_f32_16x16x32_bf16 v[130:133], v[146:149], v[180:183], v[130:133]
	v_mfma_f32_16x16x32_bf16 v[126:129], v[172:175], v[180:183], v[126:129]
	v_mfma_f32_16x16x32_bf16 v[102:105], v[146:149], v[194:197], v[102:105]
	v_mfma_f32_16x16x32_bf16 v[98:101], v[172:175], v[194:197], v[98:101]
	v_mfma_f32_16x16x32_bf16 v[86:89], v[146:149], v[202:205], v[86:89]
	v_mfma_f32_16x16x32_bf16 v[82:85], v[172:175], v[202:205], v[82:85]
	v_mfma_f32_16x16x32_bf16 v[70:73], v[146:149], v[210:213], v[70:73]
	v_mfma_f32_16x16x32_bf16 v[66:69], v[172:175], v[210:213], v[66:69]
	v_mfma_f32_16x16x32_bf16 v[130:133], v[150:153], v[184:187], v[130:133]
	v_mfma_f32_16x16x32_bf16 v[126:129], v[176:179], v[184:187], v[126:129]
	v_mfma_f32_16x16x32_bf16 v[102:105], v[150:153], v[198:201], v[102:105]
	v_mfma_f32_16x16x32_bf16 v[98:101], v[176:179], v[198:201], v[98:101]
	v_mfma_f32_16x16x32_bf16 v[86:89], v[150:153], v[206:209], v[86:89]
	v_mfma_f32_16x16x32_bf16 v[82:85], v[176:179], v[206:209], v[82:85]
	v_mfma_f32_16x16x32_bf16 v[70:73], v[150:153], v[214:217], v[70:73]
	v_mfma_f32_16x16x32_bf16 v[66:69], v[176:179], v[214:217], v[66:69]
	s_setprio 0
	s_barrier
	s_add_i32 s26, s48, s33
	v_lshl_add_u64 v[158:159], v[158:159], 0, s[82:83]
	s_mov_b32 m0, s26
	ds_read_b128 v[180:183], v193 offset:49152
	ds_read_b128 v[184:187], v193 offset:50176
	ds_read_b128 v[194:197], v193 offset:51200
	ds_read_b128 v[198:201], v193 offset:52224
	ds_read_b128 v[202:205], v193 offset:53248
	ds_read_b128 v[206:209], v193 offset:54272
	ds_read_b128 v[210:213], v193 offset:55296
	ds_read_b128 v[214:217], v193 offset:56320
	global_load_lds_dwordx4 v[158:159], off
	s_add_i32 m0, s26, 0x2000
	s_add_u32 s24, s24, 0x40080
	v_lshl_add_u64 v[158:159], v[162:163], 0, s[82:83]
	s_addc_u32 s25, s25, 0
	s_add_i32 s26, s49, s33
	global_load_lds_dwordx4 v[158:159], off
	v_lshl_add_u64 v[158:159], s[24:25], 0, v[0:1]
	s_mov_b32 m0, s26
	s_nop 0
	global_load_lds_dwordx4 v[158:159], off
	v_lshl_add_u64 v[158:159], s[24:25], 0, v[154:155]
	s_add_i32 m0, s26, 0x2000
	s_nop 0
	global_load_lds_dwordx4 v[158:159], off
	v_lshl_add_u64 v[158:159], v[188:189], 0, s[82:83]
	s_mov_b32 m0, s38
	s_nop 0
	global_load_lds_dwordx4 v[158:159], off
	v_lshl_add_u64 v[158:159], v[218:219], 0, s[82:83]
	s_mov_b32 m0, s39
	s_nop 0
	global_load_lds_dwordx4 v[158:159], off
	s_waitcnt vmcnt(8)
	s_waitcnt lgkmcnt(0)
	s_barrier
	s_setprio 1
	v_mfma_f32_16x16x32_bf16 v[62:65], v[114:117], v[180:183], v[62:65]
	v_mfma_f32_16x16x32_bf16 v[58:61], v[122:125], v[180:183], v[58:61]
	v_mfma_f32_16x16x32_bf16 v[46:49], v[114:117], v[194:197], v[46:49]
	v_mfma_f32_16x16x32_bf16 v[42:45], v[122:125], v[194:197], v[42:45]
	v_mfma_f32_16x16x32_bf16 v[30:33], v[114:117], v[202:205], v[30:33]
	v_mfma_f32_16x16x32_bf16 v[26:29], v[122:125], v[202:205], v[26:29]
	v_mfma_f32_16x16x32_bf16 v[14:17], v[114:117], v[210:213], v[14:17]
	v_mfma_f32_16x16x32_bf16 v[10:13], v[122:125], v[210:213], v[10:13]
	v_mfma_f32_16x16x32_bf16 v[62:65], v[118:121], v[184:187], v[62:65]
	v_mfma_f32_16x16x32_bf16 v[58:61], v[134:137], v[184:187], v[58:61]
	v_mfma_f32_16x16x32_bf16 v[46:49], v[118:121], v[198:201], v[46:49]
	v_mfma_f32_16x16x32_bf16 v[42:45], v[134:137], v[198:201], v[42:45]
	v_mfma_f32_16x16x32_bf16 v[30:33], v[118:121], v[206:209], v[30:33]
	v_mfma_f32_16x16x32_bf16 v[26:29], v[134:137], v[206:209], v[26:29]
	v_mfma_f32_16x16x32_bf16 v[14:17], v[118:121], v[214:217], v[14:17]
	v_mfma_f32_16x16x32_bf16 v[10:13], v[134:137], v[214:217], v[10:13]
	v_mfma_f32_16x16x32_bf16 v[54:57], v[146:149], v[180:183], v[54:57]
	v_mfma_f32_16x16x32_bf16 v[50:53], v[172:175], v[180:183], v[50:53]
	v_mfma_f32_16x16x32_bf16 v[38:41], v[146:149], v[194:197], v[38:41]
	v_mfma_f32_16x16x32_bf16 v[34:37], v[172:175], v[194:197], v[34:37]
	v_mfma_f32_16x16x32_bf16 v[22:25], v[146:149], v[202:205], v[22:25]
	v_mfma_f32_16x16x32_bf16 v[18:21], v[172:175], v[202:205], v[18:21]
	v_mfma_f32_16x16x32_bf16 v[6:9], v[146:149], v[210:213], v[6:9]
	v_mfma_f32_16x16x32_bf16 v[2:5], v[172:175], v[210:213], v[2:5]
	v_mfma_f32_16x16x32_bf16 v[54:57], v[150:153], v[184:187], v[54:57]
	v_mfma_f32_16x16x32_bf16 v[50:53], v[176:179], v[184:187], v[50:53]
	v_mfma_f32_16x16x32_bf16 v[38:41], v[150:153], v[198:201], v[38:41]
	v_mfma_f32_16x16x32_bf16 v[34:37], v[176:179], v[198:201], v[34:37]
	v_mfma_f32_16x16x32_bf16 v[22:25], v[150:153], v[206:209], v[22:25]
	v_mfma_f32_16x16x32_bf16 v[18:21], v[176:179], v[206:209], v[18:21]
	v_mfma_f32_16x16x32_bf16 v[6:9], v[150:153], v[214:217], v[6:9]
	v_mfma_f32_16x16x32_bf16 v[2:5], v[176:179], v[214:217], v[2:5]
	s_setprio 0
	s_barrier
	s_add_i32 s47, s47, 2
	s_add_u32 s22, s22, 0x100
	s_addc_u32 s23, s23, 0
	s_add_u32 s45, s45, 0x100
	s_addc_u32 s46, s46, 0
	s_cmp_gt_u32 s47, 13
	s_cbranch_scc0 .LBB0_693
	s_and_b64 vcc, exec, s[12:13]
	s_cbranch_vccz .LBB0_696
	s_barrier

.LBB0_787:
	s_add_u32 s34, s8, 0x100
	s_addc_u32 s35, s9, 0
	s_and_b64 s[36:37], s[36:37], exec
	s_cselect_b32 s39, s64, s35
	s_cselect_b32 s38, s65, s34
	s_cselect_b32 s37, s25, s69
	s_cselect_b32 s36, s66, s68
	s_add_i32 s71, 0, 0x10000
	v_add_u32_e32 v0, s71, v228
	s_add_i32 s74, 0, 0x14000
	ds_read_b128 v[130:133], v0
	ds_read_b128 v[134:137], v0 offset:1024
	ds_read_b128 v[138:141], v0 offset:2048
	ds_read_b128 v[154:157], v0 offset:3072
	v_add_u32_e32 v0, s74, v228
	ds_read_b128 v[166:169], v0
	ds_read_b128 v[170:173], v0 offset:1024
	ds_read_b128 v[174:177], v0 offset:2048
	ds_read_b128 v[178:181], v0 offset:3072
	v_lshl_add_u64 v[158:159], s[8:9], 0, v[150:151]
	s_add_i32 m0, s52, 0xc000
	ds_read_b128 v[182:185], v233
	ds_read_b128 v[186:189], v233 offset:1024
	ds_read_b128 v[190:193], v233 offset:2048
	ds_read_b128 v[194:197], v233 offset:3072
	ds_read_b128 v[198:201], v233 offset:4096
	ds_read_b128 v[202:205], v233 offset:5120
	ds_read_b128 v[206:209], v233 offset:6144
	ds_read_b128 v[210:213], v233 offset:7168
	global_load_lds_dwordx4 v[158:159], off
	v_lshl_add_u64 v[158:159], s[8:9], 0, v[152:153]
	s_add_i32 m0, s52, 0xe000
	s_nop 0
	global_load_lds_dwordx4 v[158:159], off
	s_waitcnt vmcnt(8)
	s_waitcnt lgkmcnt(0)
	s_barrier
	s_setprio 1
	v_mfma_f32_16x16x32_bf16 v[118:121], v[130:133], v[182:185], v[118:121]
	v_mfma_f32_16x16x32_bf16 v[54:57], v[138:141], v[182:185], v[54:57]
	v_mfma_f32_16x16x32_bf16 v[114:117], v[130:133], v[190:193], v[114:117]
	v_mfma_f32_16x16x32_bf16 v[50:53], v[138:141], v[190:193], v[50:53]
	v_mfma_f32_16x16x32_bf16 v[126:129], v[130:133], v[198:201], v[126:129]
	v_mfma_f32_16x16x32_bf16 v[62:65], v[138:141], v[198:201], v[62:65]
	v_mfma_f32_16x16x32_bf16 v[122:125], v[130:133], v[206:209], v[122:125]
	v_mfma_f32_16x16x32_bf16 v[58:61], v[138:141], v[206:209], v[58:61]
	v_mfma_f32_16x16x32_bf16 v[118:121], v[134:137], v[186:189], v[118:121]
	v_mfma_f32_16x16x32_bf16 v[54:57], v[154:157], v[186:189], v[54:57]
	v_mfma_f32_16x16x32_bf16 v[114:117], v[134:137], v[194:197], v[114:117]
	v_mfma_f32_16x16x32_bf16 v[50:53], v[154:157], v[194:197], v[50:53]
	v_mfma_f32_16x16x32_bf16 v[126:129], v[134:137], v[202:205], v[126:129]
	v_mfma_f32_16x16x32_bf16 v[62:65], v[154:157], v[202:205], v[62:65]
	v_mfma_f32_16x16x32_bf16 v[122:125], v[134:137], v[210:213], v[122:125]
	v_mfma_f32_16x16x32_bf16 v[58:61], v[154:157], v[210:213], v[58:61]
	v_mfma_f32_16x16x32_bf16 v[102:105], v[166:169], v[182:185], v[102:105]
	v_mfma_f32_16x16x32_bf16 v[38:41], v[174:177], v[182:185], v[38:41]
	v_mfma_f32_16x16x32_bf16 v[98:101], v[166:169], v[190:193], v[98:101]
	v_mfma_f32_16x16x32_bf16 v[34:37], v[174:177], v[190:193], v[34:37]
	v_mfma_f32_16x16x32_bf16 v[110:113], v[166:169], v[198:201], v[110:113]
	v_mfma_f32_16x16x32_bf16 v[46:49], v[174:177], v[198:201], v[46:49]
	v_mfma_f32_16x16x32_bf16 v[106:109], v[166:169], v[206:209], v[106:109]
	v_mfma_f32_16x16x32_bf16 v[42:45], v[174:177], v[206:209], v[42:45]
	v_mfma_f32_16x16x32_bf16 v[102:105], v[170:173], v[186:189], v[102:105]
	v_mfma_f32_16x16x32_bf16 v[38:41], v[178:181], v[186:189], v[38:41]
	v_mfma_f32_16x16x32_bf16 v[98:101], v[170:173], v[194:197], v[98:101]
	v_mfma_f32_16x16x32_bf16 v[34:37], v[178:181], v[194:197], v[34:37]
	v_mfma_f32_16x16x32_bf16 v[110:113], v[170:173], v[202:205], v[110:113]
	v_mfma_f32_16x16x32_bf16 v[46:49], v[178:181], v[202:205], v[46:49]
	v_mfma_f32_16x16x32_bf16 v[106:109], v[170:173], v[210:213], v[106:109]
	v_mfma_f32_16x16x32_bf16 v[42:45], v[178:181], v[210:213], v[42:45]
	s_setprio 0
	s_barrier
	s_add_i32 s8, s71, s51
	v_lshl_add_u64 v[158:159], s[36:37], 0, v[144:145]
	s_mov_b32 m0, s8
	ds_read_b128 v[182:185], v233 offset:16384
	ds_read_b128 v[186:189], v233 offset:17408
	ds_read_b128 v[190:193], v233 offset:18432
	ds_read_b128 v[194:197], v233 offset:19456
	ds_read_b128 v[198:201], v233 offset:20480
	ds_read_b128 v[202:205], v233 offset:21504
	ds_read_b128 v[206:209], v233 offset:22528
	ds_read_b128 v[210:213], v233 offset:23552
	global_load_lds_dwordx4 v[158:159], off
	s_add_i32 m0, s8, 0x2000
	s_add_u32 s8, s36, 0x40000
	v_lshl_add_u64 v[162:163], s[36:37], 0, v[148:149]
	s_addc_u32 s9, s37, 0
	s_add_i32 s71, s74, s51
	global_load_lds_dwordx4 v[162:163], off
	v_lshl_add_u64 v[214:215], s[8:9], 0, v[144:145]
	s_mov_b32 m0, s71
	v_lshl_add_u64 v[216:217], s[38:39], 0, v[146:147]
	global_load_lds_dwordx4 v[214:215], off
	v_lshl_add_u64 v[214:215], s[8:9], 0, v[148:149]
	s_add_i32 m0, s71, 0x2000
	s_nop 0
	global_load_lds_dwordx4 v[214:215], off
	v_lshl_add_u64 v[214:215], s[38:39], 0, v[142:143]
	s_mov_b32 m0, s52
	s_nop 0
	global_load_lds_dwordx4 v[214:215], off
	s_mov_b32 m0, s53
	s_nop 0
	global_load_lds_dwordx4 v[216:217], off
	s_waitcnt vmcnt(8)
	s_waitcnt lgkmcnt(0)
	s_barrier
	s_setprio 1
	v_mfma_f32_16x16x32_bf16 v[86:89], v[130:133], v[182:185], v[86:89]
	v_mfma_f32_16x16x32_bf16 v[22:25], v[138:141], v[182:185], v[22:25]
	v_mfma_f32_16x16x32_bf16 v[82:85], v[130:133], v[190:193], v[82:85]
	v_mfma_f32_16x16x32_bf16 v[18:21], v[138:141], v[190:193], v[18:21]
	v_mfma_f32_16x16x32_bf16 v[94:97], v[130:133], v[198:201], v[94:97]
	v_mfma_f32_16x16x32_bf16 v[30:33], v[138:141], v[198:201], v[30:33]
	v_mfma_f32_16x16x32_bf16 v[90:93], v[130:133], v[206:209], v[90:93]
	v_mfma_f32_16x16x32_bf16 v[26:29], v[138:141], v[206:209], v[26:29]
	v_mfma_f32_16x16x32_bf16 v[86:89], v[134:137], v[186:189], v[86:89]
	v_mfma_f32_16x16x32_bf16 v[22:25], v[154:157], v[186:189], v[22:25]
	v_mfma_f32_16x16x32_bf16 v[82:85], v[134:137], v[194:197], v[82:85]
	v_mfma_f32_16x16x32_bf16 v[18:21], v[154:157], v[194:197], v[18:21]
	v_mfma_f32_16x16x32_bf16 v[94:97], v[134:137], v[202:205], v[94:97]
	v_mfma_f32_16x16x32_bf16 v[30:33], v[154:157], v[202:205], v[30:33]
	v_mfma_f32_16x16x32_bf16 v[90:93], v[134:137], v[210:213], v[90:93]
	v_mfma_f32_16x16x32_bf16 v[26:29], v[154:157], v[210:213], v[26:29]
	v_mfma_f32_16x16x32_bf16 v[70:73], v[166:169], v[182:185], v[70:73]
	v_mfma_f32_16x16x32_bf16 v[6:9], v[174:177], v[182:185], v[6:9]
	v_mfma_f32_16x16x32_bf16 v[66:69], v[166:169], v[190:193], v[66:69]
	v_mfma_f32_16x16x32_bf16 v[2:5], v[174:177], v[190:193], v[2:5]
	v_mfma_f32_16x16x32_bf16 v[78:81], v[166:169], v[198:201], v[78:81]
	v_mfma_f32_16x16x32_bf16 v[14:17], v[174:177], v[198:201], v[14:17]
	v_mfma_f32_16x16x32_bf16 v[74:77], v[166:169], v[206:209], v[74:77]
	v_mfma_f32_16x16x32_bf16 v[10:13], v[174:177], v[206:209], v[10:13]
	v_mfma_f32_16x16x32_bf16 v[70:73], v[170:173], v[186:189], v[70:73]
	v_mfma_f32_16x16x32_bf16 v[6:9], v[178:181], v[186:189], v[6:9]
	v_mfma_f32_16x16x32_bf16 v[66:69], v[170:173], v[194:197], v[66:69]
	v_mfma_f32_16x16x32_bf16 v[2:5], v[178:181], v[194:197], v[2:5]
	v_mfma_f32_16x16x32_bf16 v[78:81], v[170:173], v[202:205], v[78:81]
	v_mfma_f32_16x16x32_bf16 v[14:17], v[178:181], v[202:205], v[14:17]
	v_mfma_f32_16x16x32_bf16 v[74:77], v[170:173], v[210:213], v[74:77]
	v_mfma_f32_16x16x32_bf16 v[10:13], v[178:181], v[210:213], v[10:13]
	s_setprio 0
	s_barrier
	s_add_i32 s71, 0, 0x18000
	v_add_u32_e32 v0, s71, v228
	s_add_i32 s74, 0, 0x1c000
	ds_read_b128 v[130:133], v0
	ds_read_b128 v[134:137], v0 offset:1024
	ds_read_b128 v[138:141], v0 offset:2048
	ds_read_b128 v[154:157], v0 offset:3072
	v_add_u32_e32 v0, s74, v228
	ds_read_b128 v[166:169], v0
	ds_read_b128 v[170:173], v0 offset:1024
	ds_read_b128 v[174:177], v0 offset:2048
	ds_read_b128 v[178:181], v0 offset:3072
	s_add_u32 s8, s38, 0x40000
	s_addc_u32 s9, s39, 0
	s_mov_b32 m0, s54
	v_lshl_add_u64 v[218:219], s[8:9], 0, v[142:143]
	ds_read_b128 v[182:185], v233 offset:32768
	ds_read_b128 v[186:189], v233 offset:33792
	ds_read_b128 v[190:193], v233 offset:34816
	ds_read_b128 v[194:197], v233 offset:35840
	ds_read_b128 v[198:201], v233 offset:36864
	ds_read_b128 v[202:205], v233 offset:37888
	ds_read_b128 v[206:209], v233 offset:38912
	ds_read_b128 v[210:213], v233 offset:39936
	global_load_lds_dwordx4 v[218:219], off
	v_lshl_add_u64 v[218:219], s[8:9], 0, v[146:147]
	s_mov_b32 m0, s55
	s_nop 0
	global_load_lds_dwordx4 v[218:219], off
	s_waitcnt vmcnt(8)
	s_waitcnt lgkmcnt(0)
	s_barrier
	s_setprio 1
	v_mfma_f32_16x16x32_bf16 v[118:121], v[130:133], v[182:185], v[118:121]
	v_mfma_f32_16x16x32_bf16 v[54:57], v[138:141], v[182:185], v[54:57]
	v_mfma_f32_16x16x32_bf16 v[114:117], v[130:133], v[190:193], v[114:117]
	v_mfma_f32_16x16x32_bf16 v[50:53], v[138:141], v[190:193], v[50:53]
	v_mfma_f32_16x16x32_bf16 v[126:129], v[130:133], v[198:201], v[126:129]
	v_mfma_f32_16x16x32_bf16 v[62:65], v[138:141], v[198:201], v[62:65]
	v_mfma_f32_16x16x32_bf16 v[122:125], v[130:133], v[206:209], v[122:125]
	v_mfma_f32_16x16x32_bf16 v[58:61], v[138:141], v[206:209], v[58:61]
	v_mfma_f32_16x16x32_bf16 v[118:121], v[134:137], v[186:189], v[118:121]
	v_mfma_f32_16x16x32_bf16 v[54:57], v[154:157], v[186:189], v[54:57]
	v_mfma_f32_16x16x32_bf16 v[114:117], v[134:137], v[194:197], v[114:117]
	v_mfma_f32_16x16x32_bf16 v[50:53], v[154:157], v[194:197], v[50:53]
	v_mfma_f32_16x16x32_bf16 v[126:129], v[134:137], v[202:205], v[126:129]
	v_mfma_f32_16x16x32_bf16 v[62:65], v[154:157], v[202:205], v[62:65]
	v_mfma_f32_16x16x32_bf16 v[122:125], v[134:137], v[210:213], v[122:125]
	v_mfma_f32_16x16x32_bf16 v[58:61], v[154:157], v[210:213], v[58:61]
	v_mfma_f32_16x16x32_bf16 v[102:105], v[166:169], v[182:185], v[102:105]
	v_mfma_f32_16x16x32_bf16 v[38:41], v[174:177], v[182:185], v[38:41]
	v_mfma_f32_16x16x32_bf16 v[98:101], v[166:169], v[190:193], v[98:101]
	v_mfma_f32_16x16x32_bf16 v[34:37], v[174:177], v[190:193], v[34:37]
	v_mfma_f32_16x16x32_bf16 v[110:113], v[166:169], v[198:201], v[110:113]
	v_mfma_f32_16x16x32_bf16 v[46:49], v[174:177], v[198:201], v[46:49]
	v_mfma_f32_16x16x32_bf16 v[106:109], v[166:169], v[206:209], v[106:109]
	v_mfma_f32_16x16x32_bf16 v[42:45], v[174:177], v[206:209], v[42:45]
	v_mfma_f32_16x16x32_bf16 v[102:105], v[170:173], v[186:189], v[102:105]
	v_mfma_f32_16x16x32_bf16 v[38:41], v[178:181], v[186:189], v[38:41]
	v_mfma_f32_16x16x32_bf16 v[98:101], v[170:173], v[194:197], v[98:101]
	v_mfma_f32_16x16x32_bf16 v[34:37], v[178:181], v[194:197], v[34:37]
	v_mfma_f32_16x16x32_bf16 v[110:113], v[170:173], v[202:205], v[110:113]
	v_mfma_f32_16x16x32_bf16 v[46:49], v[178:181], v[202:205], v[46:49]
	v_mfma_f32_16x16x32_bf16 v[106:109], v[170:173], v[210:213], v[106:109]
	v_mfma_f32_16x16x32_bf16 v[42:45], v[178:181], v[210:213], v[42:45]
	s_setprio 0
	s_barrier
	s_add_i32 s8, s71, s51
	v_lshl_add_u64 v[158:159], v[158:159], 0, s[82:83]
	s_mov_b32 m0, s8
	ds_read_b128 v[182:185], v233 offset:49152
	ds_read_b128 v[186:189], v233 offset:50176
	ds_read_b128 v[190:193], v233 offset:51200
	ds_read_b128 v[194:197], v233 offset:52224
	ds_read_b128 v[198:201], v233 offset:53248
	ds_read_b128 v[202:205], v233 offset:54272
	ds_read_b128 v[206:209], v233 offset:55296
	ds_read_b128 v[210:213], v233 offset:56320
	global_load_lds_dwordx4 v[158:159], off
	s_add_i32 m0, s8, 0x2000
	s_add_u32 s8, s36, 0x40080
	v_lshl_add_u64 v[158:159], v[162:163], 0, s[82:83]
	s_addc_u32 s9, s37, 0
	s_add_i32 s36, s74, s51
	global_load_lds_dwordx4 v[158:159], off
	v_lshl_add_u64 v[158:159], s[8:9], 0, v[144:145]
	s_mov_b32 m0, s36
	s_nop 0
	global_load_lds_dwordx4 v[158:159], off
	v_lshl_add_u64 v[158:159], s[8:9], 0, v[148:149]
	s_add_i32 m0, s36, 0x2000
	s_nop 0
	global_load_lds_dwordx4 v[158:159], off
	v_lshl_add_u64 v[158:159], v[214:215], 0, s[82:83]
	s_mov_b32 m0, s58
	s_nop 0
	global_load_lds_dwordx4 v[158:159], off
	v_lshl_add_u64 v[158:159], v[216:217], 0, s[82:83]
	s_mov_b32 m0, s59
	s_nop 0
	global_load_lds_dwordx4 v[158:159], off
	s_waitcnt vmcnt(8)
	s_waitcnt lgkmcnt(0)
	s_barrier
	s_setprio 1
	v_mfma_f32_16x16x32_bf16 v[86:89], v[130:133], v[182:185], v[86:89]
	v_mfma_f32_16x16x32_bf16 v[22:25], v[138:141], v[182:185], v[22:25]
	v_mfma_f32_16x16x32_bf16 v[82:85], v[130:133], v[190:193], v[82:85]
	v_mfma_f32_16x16x32_bf16 v[18:21], v[138:141], v[190:193], v[18:21]
	v_mfma_f32_16x16x32_bf16 v[94:97], v[130:133], v[198:201], v[94:97]
	v_mfma_f32_16x16x32_bf16 v[30:33], v[138:141], v[198:201], v[30:33]
	v_mfma_f32_16x16x32_bf16 v[90:93], v[130:133], v[206:209], v[90:93]
	v_mfma_f32_16x16x32_bf16 v[26:29], v[138:141], v[206:209], v[26:29]
	v_mfma_f32_16x16x32_bf16 v[86:89], v[134:137], v[186:189], v[86:89]
	v_mfma_f32_16x16x32_bf16 v[22:25], v[154:157], v[186:189], v[22:25]
	v_mfma_f32_16x16x32_bf16 v[82:85], v[134:137], v[194:197], v[82:85]
	v_mfma_f32_16x16x32_bf16 v[18:21], v[154:157], v[194:197], v[18:21]
	v_mfma_f32_16x16x32_bf16 v[94:97], v[134:137], v[202:205], v[94:97]
	v_mfma_f32_16x16x32_bf16 v[30:33], v[154:157], v[202:205], v[30:33]
	v_mfma_f32_16x16x32_bf16 v[90:93], v[134:137], v[210:213], v[90:93]
	v_mfma_f32_16x16x32_bf16 v[26:29], v[154:157], v[210:213], v[26:29]
	v_mfma_f32_16x16x32_bf16 v[70:73], v[166:169], v[182:185], v[70:73]
	v_mfma_f32_16x16x32_bf16 v[6:9], v[174:177], v[182:185], v[6:9]
	v_mfma_f32_16x16x32_bf16 v[66:69], v[166:169], v[190:193], v[66:69]
	v_mfma_f32_16x16x32_bf16 v[2:5], v[174:177], v[190:193], v[2:5]
	v_mfma_f32_16x16x32_bf16 v[78:81], v[166:169], v[198:201], v[78:81]
	v_mfma_f32_16x16x32_bf16 v[14:17], v[174:177], v[198:201], v[14:17]
	v_mfma_f32_16x16x32_bf16 v[74:77], v[166:169], v[206:209], v[74:77]
	v_mfma_f32_16x16x32_bf16 v[10:13], v[174:177], v[206:209], v[10:13]
	v_mfma_f32_16x16x32_bf16 v[70:73], v[170:173], v[186:189], v[70:73]
	v_mfma_f32_16x16x32_bf16 v[6:9], v[178:181], v[186:189], v[6:9]
	v_mfma_f32_16x16x32_bf16 v[66:69], v[170:173], v[194:197], v[66:69]
	v_mfma_f32_16x16x32_bf16 v[2:5], v[178:181], v[194:197], v[2:5]
	v_mfma_f32_16x16x32_bf16 v[78:81], v[170:173], v[202:205], v[78:81]
	v_mfma_f32_16x16x32_bf16 v[14:17], v[178:181], v[202:205], v[14:17]
	v_mfma_f32_16x16x32_bf16 v[74:77], v[170:173], v[210:213], v[74:77]
	v_mfma_f32_16x16x32_bf16 v[10:13], v[178:181], v[210:213], v[10:13]
	s_setprio 0
	s_barrier
	s_add_i32 s70, s70, 2
	s_add_u32 s68, s68, 0x100
	s_addc_u32 s69, s69, 0
	s_cmp_gt_u32 s70, 13
	s_cbranch_scc1 .LBB0_789
	s_mov_b64 s[8:9], s[34:35]
	s_branch .LBB0_782

.LBB0_966:
	s_add_u32 s20, s18, 0x100
	s_addc_u32 s21, s19, 0
	s_add_i32 s46, 0, 0x10000
	s_cmp_eq_u32 s45, 40
	s_cselect_b32 s25, s9, s21
	s_cselect_b32 s24, s8, s20
	s_cselect_b32 s23, s17, s44
	s_cselect_b32 s22, s16, s43
	s_add_i32 s47, 0, 0x14000
	v_add_u32_e32 v134, s46, v191
	v_add_u32_e32 v158, s47, v191
	ds_read_b128 v[114:117], v134
	ds_read_b128 v[118:121], v134 offset:1024
	ds_read_b128 v[122:125], v134 offset:2048
	ds_read_b128 v[134:137], v134 offset:3072
	ds_read_b128 v[146:149], v158
	ds_read_b128 v[150:153], v158 offset:1024
	ds_read_b128 v[172:175], v158 offset:2048
	ds_read_b128 v[176:179], v158 offset:3072
	v_lshl_add_u64 v[158:159], s[18:19], 0, v[168:169]
	s_add_i32 m0, s31, 0xc000
	ds_read_b128 v[180:183], v193
	ds_read_b128 v[184:187], v193 offset:1024
	ds_read_b128 v[194:197], v193 offset:2048
	ds_read_b128 v[198:201], v193 offset:3072
	ds_read_b128 v[202:205], v193 offset:4096
	ds_read_b128 v[206:209], v193 offset:5120
	ds_read_b128 v[210:213], v193 offset:6144
	ds_read_b128 v[214:217], v193 offset:7168
	global_load_lds_dwordx4 v[158:159], off
	v_lshl_add_u64 v[158:159], s[18:19], 0, v[170:171]
	s_add_i32 m0, s31, 0xe000
	s_nop 0
	global_load_lds_dwordx4 v[158:159], off
	s_waitcnt vmcnt(8)
	s_waitcnt lgkmcnt(0)
	s_barrier
	s_setprio 1
	v_mfma_f32_16x16x32_bf16 v[142:145], v[114:117], v[180:183], v[142:145]
	v_mfma_f32_16x16x32_bf16 v[138:141], v[122:125], v[180:183], v[138:141]
	v_mfma_f32_16x16x32_bf16 v[110:113], v[114:117], v[194:197], v[110:113]
	v_mfma_f32_16x16x32_bf16 v[106:109], v[122:125], v[194:197], v[106:109]
	v_mfma_f32_16x16x32_bf16 v[94:97], v[114:117], v[202:205], v[94:97]
	v_mfma_f32_16x16x32_bf16 v[90:93], v[122:125], v[202:205], v[90:93]
	v_mfma_f32_16x16x32_bf16 v[78:81], v[114:117], v[210:213], v[78:81]
	v_mfma_f32_16x16x32_bf16 v[74:77], v[122:125], v[210:213], v[74:77]
	v_mfma_f32_16x16x32_bf16 v[142:145], v[118:121], v[184:187], v[142:145]
	v_mfma_f32_16x16x32_bf16 v[138:141], v[134:137], v[184:187], v[138:141]
	v_mfma_f32_16x16x32_bf16 v[110:113], v[118:121], v[198:201], v[110:113]
	v_mfma_f32_16x16x32_bf16 v[106:109], v[134:137], v[198:201], v[106:109]
	v_mfma_f32_16x16x32_bf16 v[94:97], v[118:121], v[206:209], v[94:97]
	v_mfma_f32_16x16x32_bf16 v[90:93], v[134:137], v[206:209], v[90:93]
	v_mfma_f32_16x16x32_bf16 v[78:81], v[118:121], v[214:217], v[78:81]
	v_mfma_f32_16x16x32_bf16 v[74:77], v[134:137], v[214:217], v[74:77]
	v_mfma_f32_16x16x32_bf16 v[130:133], v[146:149], v[180:183], v[130:133]
	v_mfma_f32_16x16x32_bf16 v[126:129], v[172:175], v[180:183], v[126:129]
	v_mfma_f32_16x16x32_bf16 v[102:105], v[146:149], v[194:197], v[102:105]
	v_mfma_f32_16x16x32_bf16 v[98:101], v[172:175], v[194:197], v[98:101]
	v_mfma_f32_16x16x32_bf16 v[86:89], v[146:149], v[202:205], v[86:89]
	v_mfma_f32_16x16x32_bf16 v[82:85], v[172:175], v[202:205], v[82:85]
	v_mfma_f32_16x16x32_bf16 v[70:73], v[146:149], v[210:213], v[70:73]
	v_mfma_f32_16x16x32_bf16 v[66:69], v[172:175], v[210:213], v[66:69]
	v_mfma_f32_16x16x32_bf16 v[130:133], v[150:153], v[184:187], v[130:133]
	v_mfma_f32_16x16x32_bf16 v[126:129], v[176:179], v[184:187], v[126:129]
	v_mfma_f32_16x16x32_bf16 v[102:105], v[150:153], v[198:201], v[102:105]
	v_mfma_f32_16x16x32_bf16 v[98:101], v[176:179], v[198:201], v[98:101]
	v_mfma_f32_16x16x32_bf16 v[86:89], v[150:153], v[206:209], v[86:89]
	v_mfma_f32_16x16x32_bf16 v[82:85], v[176:179], v[206:209], v[82:85]
	v_mfma_f32_16x16x32_bf16 v[70:73], v[150:153], v[214:217], v[70:73]
	v_mfma_f32_16x16x32_bf16 v[66:69], v[176:179], v[214:217], v[66:69]
	s_setprio 0
	s_barrier
	s_add_i32 s18, s46, s30
	v_lshl_add_u64 v[158:159], s[22:23], 0, v[0:1]
	s_mov_b32 m0, s18
	ds_read_b128 v[180:183], v193 offset:16384
	ds_read_b128 v[184:187], v193 offset:17408
	ds_read_b128 v[194:197], v193 offset:18432
	ds_read_b128 v[198:201], v193 offset:19456
	ds_read_b128 v[202:205], v193 offset:20480
	ds_read_b128 v[206:209], v193 offset:21504
	ds_read_b128 v[210:213], v193 offset:22528
	ds_read_b128 v[214:217], v193 offset:23552
	global_load_lds_dwordx4 v[158:159], off
	s_add_i32 m0, s18, 0x2000
	s_add_u32 s18, s22, 0xb0000
	v_lshl_add_u64 v[162:163], s[22:23], 0, v[154:155]
	s_addc_u32 s19, s23, 0
	s_add_i32 s46, s47, s30
	global_load_lds_dwordx4 v[162:163], off
	v_lshl_add_u64 v[188:189], s[18:19], 0, v[0:1]
	s_mov_b32 m0, s46
	v_lshl_add_u64 v[218:219], s[24:25], 0, v[156:157]
	global_load_lds_dwordx4 v[188:189], off
	v_lshl_add_u64 v[188:189], s[18:19], 0, v[154:155]
	s_add_i32 m0, s46, 0x2000
	s_nop 0
	global_load_lds_dwordx4 v[188:189], off
	v_lshl_add_u64 v[188:189], s[24:25], 0, v[166:167]
	s_mov_b32 m0, s31
	s_nop 0
	global_load_lds_dwordx4 v[188:189], off
	s_mov_b32 m0, s33
	s_nop 0
	global_load_lds_dwordx4 v[218:219], off
	s_waitcnt vmcnt(8)
	s_waitcnt lgkmcnt(0)
	s_barrier
	s_setprio 1
	v_mfma_f32_16x16x32_bf16 v[62:65], v[114:117], v[180:183], v[62:65]
	v_mfma_f32_16x16x32_bf16 v[58:61], v[122:125], v[180:183], v[58:61]
	v_mfma_f32_16x16x32_bf16 v[46:49], v[114:117], v[194:197], v[46:49]
	v_mfma_f32_16x16x32_bf16 v[42:45], v[122:125], v[194:197], v[42:45]
	v_mfma_f32_16x16x32_bf16 v[30:33], v[114:117], v[202:205], v[30:33]
	v_mfma_f32_16x16x32_bf16 v[26:29], v[122:125], v[202:205], v[26:29]
	v_mfma_f32_16x16x32_bf16 v[14:17], v[114:117], v[210:213], v[14:17]
	v_mfma_f32_16x16x32_bf16 v[10:13], v[122:125], v[210:213], v[10:13]
	v_mfma_f32_16x16x32_bf16 v[62:65], v[118:121], v[184:187], v[62:65]
	v_mfma_f32_16x16x32_bf16 v[58:61], v[134:137], v[184:187], v[58:61]
	v_mfma_f32_16x16x32_bf16 v[46:49], v[118:121], v[198:201], v[46:49]
	v_mfma_f32_16x16x32_bf16 v[42:45], v[134:137], v[198:201], v[42:45]
	v_mfma_f32_16x16x32_bf16 v[30:33], v[118:121], v[206:209], v[30:33]
	v_mfma_f32_16x16x32_bf16 v[26:29], v[134:137], v[206:209], v[26:29]
	v_mfma_f32_16x16x32_bf16 v[14:17], v[118:121], v[214:217], v[14:17]
	v_mfma_f32_16x16x32_bf16 v[10:13], v[134:137], v[214:217], v[10:13]
	v_mfma_f32_16x16x32_bf16 v[54:57], v[146:149], v[180:183], v[54:57]
	v_mfma_f32_16x16x32_bf16 v[50:53], v[172:175], v[180:183], v[50:53]
	v_mfma_f32_16x16x32_bf16 v[38:41], v[146:149], v[194:197], v[38:41]
	v_mfma_f32_16x16x32_bf16 v[34:37], v[172:175], v[194:197], v[34:37]
	v_mfma_f32_16x16x32_bf16 v[22:25], v[146:149], v[202:205], v[22:25]
	v_mfma_f32_16x16x32_bf16 v[18:21], v[172:175], v[202:205], v[18:21]
	v_mfma_f32_16x16x32_bf16 v[6:9], v[146:149], v[210:213], v[6:9]
	v_mfma_f32_16x16x32_bf16 v[2:5], v[172:175], v[210:213], v[2:5]
	v_mfma_f32_16x16x32_bf16 v[54:57], v[150:153], v[184:187], v[54:57]
	v_mfma_f32_16x16x32_bf16 v[50:53], v[176:179], v[184:187], v[50:53]
	v_mfma_f32_16x16x32_bf16 v[38:41], v[150:153], v[198:201], v[38:41]
	v_mfma_f32_16x16x32_bf16 v[34:37], v[176:179], v[198:201], v[34:37]
	v_mfma_f32_16x16x32_bf16 v[22:25], v[150:153], v[206:209], v[22:25]
	v_mfma_f32_16x16x32_bf16 v[18:21], v[176:179], v[206:209], v[18:21]
	v_mfma_f32_16x16x32_bf16 v[6:9], v[150:153], v[214:217], v[6:9]
	v_mfma_f32_16x16x32_bf16 v[2:5], v[176:179], v[214:217], v[2:5]
	s_setprio 0
	s_barrier
	s_add_i32 s46, 0, 0x18000
	s_add_i32 s47, 0, 0x1c000
	v_add_u32_e32 v134, s46, v191
	v_add_u32_e32 v176, s47, v191
	ds_read_b128 v[114:117], v134
	ds_read_b128 v[118:121], v134 offset:1024
	ds_read_b128 v[122:125], v134 offset:2048
	ds_read_b128 v[134:137], v134 offset:3072
	ds_read_b128 v[146:149], v176
	ds_read_b128 v[150:153], v176 offset:1024
	ds_read_b128 v[172:175], v176 offset:2048
	ds_read_b128 v[176:179], v176 offset:3072
	s_add_u32 s18, s24, 0xb0000
	s_addc_u32 s19, s25, 0
	s_mov_b32 m0, s34
	v_lshl_add_u64 v[220:221], s[18:19], 0, v[166:167]
	ds_read_b128 v[180:183], v193 offset:32768
	ds_read_b128 v[184:187], v193 offset:33792
	ds_read_b128 v[194:197], v193 offset:34816
	ds_read_b128 v[198:201], v193 offset:35840
	ds_read_b128 v[202:205], v193 offset:36864
	ds_read_b128 v[206:209], v193 offset:37888
	ds_read_b128 v[210:213], v193 offset:38912
	ds_read_b128 v[214:217], v193 offset:39936
	global_load_lds_dwordx4 v[220:221], off
	v_lshl_add_u64 v[220:221], s[18:19], 0, v[156:157]
	s_mov_b32 m0, s35
	s_nop 0
	global_load_lds_dwordx4 v[220:221], off
	s_waitcnt vmcnt(8)
	s_waitcnt lgkmcnt(0)
	s_barrier
	s_setprio 1
	v_mfma_f32_16x16x32_bf16 v[142:145], v[114:117], v[180:183], v[142:145]
	v_mfma_f32_16x16x32_bf16 v[138:141], v[122:125], v[180:183], v[138:141]
	v_mfma_f32_16x16x32_bf16 v[110:113], v[114:117], v[194:197], v[110:113]
	v_mfma_f32_16x16x32_bf16 v[106:109], v[122:125], v[194:197], v[106:109]
	v_mfma_f32_16x16x32_bf16 v[94:97], v[114:117], v[202:205], v[94:97]
	v_mfma_f32_16x16x32_bf16 v[90:93], v[122:125], v[202:205], v[90:93]
	v_mfma_f32_16x16x32_bf16 v[78:81], v[114:117], v[210:213], v[78:81]
	v_mfma_f32_16x16x32_bf16 v[74:77], v[122:125], v[210:213], v[74:77]
	v_mfma_f32_16x16x32_bf16 v[142:145], v[118:121], v[184:187], v[142:145]
	v_mfma_f32_16x16x32_bf16 v[138:141], v[134:137], v[184:187], v[138:141]
	v_mfma_f32_16x16x32_bf16 v[110:113], v[118:121], v[198:201], v[110:113]
	v_mfma_f32_16x16x32_bf16 v[106:109], v[134:137], v[198:201], v[106:109]
	v_mfma_f32_16x16x32_bf16 v[94:97], v[118:121], v[206:209], v[94:97]
	v_mfma_f32_16x16x32_bf16 v[90:93], v[134:137], v[206:209], v[90:93]
	v_mfma_f32_16x16x32_bf16 v[78:81], v[118:121], v[214:217], v[78:81]
	v_mfma_f32_16x16x32_bf16 v[74:77], v[134:137], v[214:217], v[74:77]
	v_mfma_f32_16x16x32_bf16 v[130:133], v[146:149], v[180:183], v[130:133]
	v_mfma_f32_16x16x32_bf16 v[126:129], v[172:175], v[180:183], v[126:129]
	v_mfma_f32_16x16x32_bf16 v[102:105], v[146:149], v[194:197], v[102:105]
	v_mfma_f32_16x16x32_bf16 v[98:101], v[172:175], v[194:197], v[98:101]
	v_mfma_f32_16x16x32_bf16 v[86:89], v[146:149], v[202:205], v[86:89]
	v_mfma_f32_16x16x32_bf16 v[82:85], v[172:175], v[202:205], v[82:85]
	v_mfma_f32_16x16x32_bf16 v[70:73], v[146:149], v[210:213], v[70:73]
	v_mfma_f32_16x16x32_bf16 v[66:69], v[172:175], v[210:213], v[66:69]
	v_mfma_f32_16x16x32_bf16 v[130:133], v[150:153], v[184:187], v[130:133]
	v_mfma_f32_16x16x32_bf16 v[126:129], v[176:179], v[184:187], v[126:129]
	v_mfma_f32_16x16x32_bf16 v[102:105], v[150:153], v[198:201], v[102:105]
	v_mfma_f32_16x16x32_bf16 v[98:101], v[176:179], v[198:201], v[98:101]
	v_mfma_f32_16x16x32_bf16 v[86:89], v[150:153], v[206:209], v[86:89]
	v_mfma_f32_16x16x32_bf16 v[82:85], v[176:179], v[206:209], v[82:85]
	v_mfma_f32_16x16x32_bf16 v[70:73], v[150:153], v[214:217], v[70:73]
	v_mfma_f32_16x16x32_bf16 v[66:69], v[176:179], v[214:217], v[66:69]
	s_setprio 0
	s_barrier
	s_add_i32 s18, s46, s30
	v_lshl_add_u64 v[158:159], v[158:159], 0, s[82:83]
	s_mov_b32 m0, s18
	ds_read_b128 v[180:183], v193 offset:49152
	ds_read_b128 v[184:187], v193 offset:50176
	ds_read_b128 v[194:197], v193 offset:51200
	ds_read_b128 v[198:201], v193 offset:52224
	ds_read_b128 v[202:205], v193 offset:53248
	ds_read_b128 v[206:209], v193 offset:54272
	ds_read_b128 v[210:213], v193 offset:55296
	ds_read_b128 v[214:217], v193 offset:56320
	global_load_lds_dwordx4 v[158:159], off
	s_add_i32 m0, s18, 0x2000
	s_add_u32 s18, s22, 0xb0080
	v_lshl_add_u64 v[158:159], v[162:163], 0, s[82:83]
	s_addc_u32 s19, s23, 0
	s_add_i32 s22, s47, s30
	global_load_lds_dwordx4 v[158:159], off
	v_lshl_add_u64 v[158:159], s[18:19], 0, v[0:1]
	s_mov_b32 m0, s22
	s_nop 0
	global_load_lds_dwordx4 v[158:159], off
	v_lshl_add_u64 v[158:159], s[18:19], 0, v[154:155]
	s_add_i32 m0, s22, 0x2000
	s_nop 0
	global_load_lds_dwordx4 v[158:159], off
	v_lshl_add_u64 v[158:159], v[188:189], 0, s[82:83]
	s_mov_b32 m0, s36
	s_nop 0
	global_load_lds_dwordx4 v[158:159], off
	v_lshl_add_u64 v[158:159], v[218:219], 0, s[82:83]
	s_mov_b32 m0, s37
	s_nop 0
	global_load_lds_dwordx4 v[158:159], off
	s_waitcnt vmcnt(8)
	s_waitcnt lgkmcnt(0)
	s_barrier
	s_setprio 1
	v_mfma_f32_16x16x32_bf16 v[62:65], v[114:117], v[180:183], v[62:65]
	v_mfma_f32_16x16x32_bf16 v[58:61], v[122:125], v[180:183], v[58:61]
	v_mfma_f32_16x16x32_bf16 v[46:49], v[114:117], v[194:197], v[46:49]
	v_mfma_f32_16x16x32_bf16 v[42:45], v[122:125], v[194:197], v[42:45]
	v_mfma_f32_16x16x32_bf16 v[30:33], v[114:117], v[202:205], v[30:33]
	v_mfma_f32_16x16x32_bf16 v[26:29], v[122:125], v[202:205], v[26:29]
	v_mfma_f32_16x16x32_bf16 v[14:17], v[114:117], v[210:213], v[14:17]
	v_mfma_f32_16x16x32_bf16 v[10:13], v[122:125], v[210:213], v[10:13]
	v_mfma_f32_16x16x32_bf16 v[62:65], v[118:121], v[184:187], v[62:65]
	v_mfma_f32_16x16x32_bf16 v[58:61], v[134:137], v[184:187], v[58:61]
	v_mfma_f32_16x16x32_bf16 v[46:49], v[118:121], v[198:201], v[46:49]
	v_mfma_f32_16x16x32_bf16 v[42:45], v[134:137], v[198:201], v[42:45]
	v_mfma_f32_16x16x32_bf16 v[30:33], v[118:121], v[206:209], v[30:33]
	v_mfma_f32_16x16x32_bf16 v[26:29], v[134:137], v[206:209], v[26:29]
	v_mfma_f32_16x16x32_bf16 v[14:17], v[118:121], v[214:217], v[14:17]
	v_mfma_f32_16x16x32_bf16 v[10:13], v[134:137], v[214:217], v[10:13]
	v_mfma_f32_16x16x32_bf16 v[54:57], v[146:149], v[180:183], v[54:57]
	v_mfma_f32_16x16x32_bf16 v[50:53], v[172:175], v[180:183], v[50:53]
	v_mfma_f32_16x16x32_bf16 v[38:41], v[146:149], v[194:197], v[38:41]
	v_mfma_f32_16x16x32_bf16 v[34:37], v[172:175], v[194:197], v[34:37]
	v_mfma_f32_16x16x32_bf16 v[22:25], v[146:149], v[202:205], v[22:25]
	v_mfma_f32_16x16x32_bf16 v[18:21], v[172:175], v[202:205], v[18:21]
	v_mfma_f32_16x16x32_bf16 v[6:9], v[146:149], v[210:213], v[6:9]
	v_mfma_f32_16x16x32_bf16 v[2:5], v[172:175], v[210:213], v[2:5]
	v_mfma_f32_16x16x32_bf16 v[54:57], v[150:153], v[184:187], v[54:57]
	v_mfma_f32_16x16x32_bf16 v[50:53], v[176:179], v[184:187], v[50:53]
	v_mfma_f32_16x16x32_bf16 v[38:41], v[150:153], v[198:201], v[38:41]
	v_mfma_f32_16x16x32_bf16 v[34:37], v[176:179], v[198:201], v[34:37]
	v_mfma_f32_16x16x32_bf16 v[22:25], v[150:153], v[206:209], v[22:25]
	v_mfma_f32_16x16x32_bf16 v[18:21], v[176:179], v[206:209], v[18:21]
	v_mfma_f32_16x16x32_bf16 v[6:9], v[150:153], v[214:217], v[6:9]
	v_mfma_f32_16x16x32_bf16 v[2:5], v[176:179], v[214:217], v[2:5]
	s_setprio 0
	s_barrier
	s_add_i32 s45, s45, 2
	s_add_u32 s43, s43, 0x100
	s_addc_u32 s44, s44, 0
	s_cmp_gt_u32 s45, 41
	s_mov_b64 s[18:19], s[20:21]
	s_cbranch_scc0 .LBB0_966
	s_and_b64 vcc, exec, s[14:15]
	s_cbranch_vccz .LBB0_969
	s_barrier
